# scan: next chunk's preparation (register-renamed) issued inside the 32-step block's idle slots; only the two exec-masked tails stay after the block
# speedup vs baseline: 1.0165x; 1.0043x over previous
; #define LAS __attribute__((address_space(3)))
; __device__ __forceinline__ float row16_sum(float x) { x += dpp_mov<0xB1>(x); x += dpp_mov<0x4E>(x); x += dpp_mov<0x124>(x); x += dpp_mov<0x128>(x); return x; }
; __device__ __forceinline__ void scan_phase(const KAS Args& a, LAS unsigned char* lds, int i, const int tid_, const int bid, const int nblk) {
;     ...
;                 for (int t = 0; t < TC; ++t) {
;                     f32x4 kk4n = kk4, nb4n = nb4, w4n = w4, k4n = k4, r4n = r4; float vn = v;
;                     if (t + 1 < TC) { const LAS float* sn = sb + (t + 1) * SST;
;                         kk4n = *(const LAS f32x4*)(sn); nb4n = *(const LAS f32x4*)(sn + 64); w4n = *(const LAS f32x4*)(sn + 128); k4n = *(const LAS f32x4*)(sn + 192); r4n = *(const LAS f32x4*)(sn + 256); vn = vb[(t + 1) * SST]; }
;                     __builtin_amdgcn_sched_barrier(0x6);
;                     float sa = fmaf(S[3], kk4[3], fmaf(S[2], kk4[2], fmaf(S[1], kk4[1], S[0] * kk4[0])));
;                     const f32x4 Tm = S * w4 + k4 * v;
;                     sa = row16_sum(sa);
;                     S = Tm + nb4 * sa;
;                     float y = fmaf(S[3], r4[3], fmaf(S[2], r4[2], fmaf(S[1], r4[1], S[0] * r4[0]))); y = row16_sum(y);
;                     ysel = (cgp == (t & 15)) ? y : ysel;
;                     if ((t & 15) == 15) yb[(t - 15 + cgp) * 32 + rl] = ysel;
;                     kk4 = kk4n; nb4 = nb4n; w4 = w4n; k4 = k4n; r4 = r4n; v = vn; }
.LBB0_190:
	s_and_b32 s2, s67, 1
	s_mul_i32 s3, s2, 0xb000
	s_add_i32 s3, s94, s3
	v_add_u32_e32 v124, s3, v114
	v_add_u32_e32 v110, s3, v120
	ds_read_b128 v[136:139], v124 offset:0
	ds_read_b128 v[140:143], v124 offset:256
	ds_read_b128 v[144:147], v124 offset:512
	ds_read_b128 v[148:151], v124 offset:768
	ds_read_b128 v[152:155], v124 offset:1024
	ds_read_b32 v156, v110 offset:1280
	ds_read_b128 v[160:163], v124 offset:1408
	ds_read_b128 v[164:167], v124 offset:1664
	ds_read_b128 v[168:171], v124 offset:1920
	ds_read_b128 v[172:175], v124 offset:2176
	ds_read_b128 v[176:179], v124 offset:2432
	ds_read_b32 v158, v110 offset:2688
	ds_read_b128 v[188:191], v124 offset:2816
	ds_read_b128 v[192:195], v124 offset:3072
	ds_read_b128 v[196:199], v124 offset:3328
	ds_read_b128 v[200:203], v124 offset:3584
	ds_read_b128 v[204:207], v124 offset:3840
	ds_read_b32 v208, v110 offset:4096
	s_lshl_b32 s2, s2, 12
	s_add_i32 s63, s64, s2
	s_add_i32 s62, s67, 1
	s_andn2_b64 vcc, exec, s[60:61]
	s_mov_b32 s8, 0xaaaaaaaa
	s_mov_b32 s9, 0xaaaaaaaa
	s_mov_b32 s10, 0xcccccccc
	s_mov_b32 s11, 0xcccccccc
	s_mov_b32 s12, 0xf0f0f0f0
	s_mov_b32 s13, 0xf0f0f0f0
	s_mov_b32 s14, 0xff00ff00
	s_mov_b32 s15, 0xff00ff00
	v_add3_u32 v122, s63, v120, v118
	s_waitcnt lgkmcnt(12)
	v_mul_f32_e32 v44, v36, v136
	v_fmac_f32_e32 v44, v37, v137
	v_fmac_f32_e32 v44, v38, v138
	v_fmac_f32_e32 v44, v39, v139
	v_pk_mul_f32 v[40:41], v[148:149], v[156:157] op_sel_hi:[1,0]
	v_pk_mul_f32 v[42:43], v[150:151], v[156:157] op_sel_hi:[1,0]
	v_add_f32_dpp v2, v44, v44 quad_perm:[1,0,3,2] row_mask:0xf bank_mask:0xf bound_ctrl:1
	v_pk_fma_f32 v[40:41], v[36:37], v[144:145], v[40:41]
	v_pk_fma_f32 v[42:43], v[38:39], v[146:147], v[42:43]
	v_add_f32_dpp v2, v2, v2 quad_perm:[2,3,0,1] row_mask:0xf bank_mask:0xf bound_ctrl:1
	s_nop 0
	s_nop 0
	v_add_f32_dpp v2, v2, v2 row_ror:4 row_mask:0xf bank_mask:0xf bound_ctrl:1
	s_nop 0
	s_nop 0
	v_add_f32_dpp v2, v2, v2 row_ror:8 row_mask:0xf bank_mask:0xf bound_ctrl:1
	s_waitcnt lgkmcnt(6)
	v_pk_fma_f32 v[36:37], v[140:141], v[2:3], v[40:41] op_sel_hi:[1,0,1]
	v_pk_fma_f32 v[38:39], v[142:143], v[2:3], v[42:43] op_sel_hi:[1,0,1]
	v_mul_f32_e32 v44, v36, v160
	v_mul_f32_e32 v45, v152, v36
	v_fmac_f32_e32 v44, v37, v161
	v_fmac_f32_e32 v45, v37, v153
	v_fmac_f32_e32 v44, v38, v162
	v_fmac_f32_e32 v45, v38, v154
	v_fmac_f32_e32 v44, v39, v163
	v_fmac_f32_e32 v45, v39, v155
	v_pk_mul_f32 v[40:41], v[172:173], v[158:159] op_sel_hi:[1,0]
	v_pk_mul_f32 v[42:43], v[174:175], v[158:159] op_sel_hi:[1,0]
	v_add_f32_dpp v2, v44, v44 quad_perm:[1,0,3,2] row_mask:0xf bank_mask:0xf bound_ctrl:1
	v_pk_fma_f32 v[40:41], v[36:37], v[168:169], v[40:41]
	v_pk_fma_f32 v[42:43], v[38:39], v[170:171], v[42:43]
	v_add_f32_dpp v2, v2, v2 quad_perm:[2,3,0,1] row_mask:0xf bank_mask:0xf bound_ctrl:1
	ds_read_b128 v[136:139], v124 offset:4224
	ds_read_b128 v[140:143], v124 offset:4480
	ds_read_b128 v[144:147], v124 offset:4736
	v_add_f32_dpp v2, v2, v2 row_ror:4 row_mask:0xf bank_mask:0xf bound_ctrl:1
	ds_read_b128 v[148:151], v124 offset:4992
	ds_read_b128 v[152:155], v124 offset:5248
	ds_read_b32 v156, v110 offset:5504
	v_add_f32_dpp v2, v2, v2 row_ror:8 row_mask:0xf bank_mask:0xf bound_ctrl:1
	s_waitcnt lgkmcnt(6)
	v_pk_fma_f32 v[36:37], v[164:165], v[2:3], v[40:41] op_sel_hi:[1,0,1]
	v_pk_fma_f32 v[38:39], v[166:167], v[2:3], v[42:43] op_sel_hi:[1,0,1]
	v_mul_f32_e32 v44, v36, v188
	v_mul_f32_e32 v46, v176, v36
	v_fmac_f32_e32 v44, v37, v189
	v_fmac_f32_e32 v46, v37, v177
	v_fmac_f32_e32 v44, v38, v190
	v_fmac_f32_e32 v46, v38, v178
	v_fmac_f32_e32 v44, v39, v191
	v_fmac_f32_e32 v46, v39, v179
	v_pk_mul_f32 v[40:41], v[200:201], v[208:209] op_sel_hi:[1,0]
	v_pk_mul_f32 v[42:43], v[202:203], v[208:209] op_sel_hi:[1,0]
	v_add_f32_dpp v2, v44, v44 quad_perm:[1,0,3,2] row_mask:0xf bank_mask:0xf bound_ctrl:1
	v_pk_fma_f32 v[40:41], v[36:37], v[196:197], v[40:41]
	v_pk_fma_f32 v[42:43], v[38:39], v[198:199], v[42:43]
	v_add_f32_dpp v2, v2, v2 quad_perm:[2,3,0,1] row_mask:0xf bank_mask:0xf bound_ctrl:1
	ds_read_b128 v[160:163], v124 offset:5632
	ds_read_b128 v[164:167], v124 offset:5888
	ds_read_b128 v[168:171], v124 offset:6144
	v_add_f32_dpp v2, v2, v2 row_ror:4 row_mask:0xf bank_mask:0xf bound_ctrl:1
	ds_read_b128 v[172:175], v124 offset:6400
	ds_read_b128 v[176:179], v124 offset:6656
	ds_read_b32 v158, v110 offset:6912
	v_add_f32_dpp v2, v2, v2 row_ror:8 row_mask:0xf bank_mask:0xf bound_ctrl:1
	v_cndmask_b32_e64 v56, v45, v46, s[8:9]
	v_cndmask_b32_e64 v57, v46, v45, s[8:9]
	s_waitcnt lgkmcnt(6)
	v_pk_fma_f32 v[36:37], v[192:193], v[2:3], v[40:41] op_sel_hi:[1,0,1]
	v_pk_fma_f32 v[38:39], v[194:195], v[2:3], v[42:43] op_sel_hi:[1,0,1]
	v_add_f32_dpp v47, v57, v56 quad_perm:[1,0,3,2] row_mask:0xf bank_mask:0xf bound_ctrl:1
	v_mul_f32_e32 v44, v36, v136
	v_mul_f32_e32 v48, v204, v36
	v_fmac_f32_e32 v44, v37, v137
	v_fmac_f32_e32 v48, v37, v205
	v_fmac_f32_e32 v44, v38, v138
	v_fmac_f32_e32 v48, v38, v206
	v_fmac_f32_e32 v44, v39, v139
	v_fmac_f32_e32 v48, v39, v207
	v_pk_mul_f32 v[40:41], v[148:149], v[156:157] op_sel_hi:[1,0]
	v_pk_mul_f32 v[42:43], v[150:151], v[156:157] op_sel_hi:[1,0]
	v_add_f32_dpp v2, v44, v44 quad_perm:[1,0,3,2] row_mask:0xf bank_mask:0xf bound_ctrl:1
	v_pk_fma_f32 v[40:41], v[36:37], v[144:145], v[40:41]
	v_pk_fma_f32 v[42:43], v[38:39], v[146:147], v[42:43]
	v_add_f32_dpp v2, v2, v2 quad_perm:[2,3,0,1] row_mask:0xf bank_mask:0xf bound_ctrl:1
	ds_read_b128 v[188:191], v124 offset:7040
	ds_read_b128 v[192:195], v124 offset:7296
	ds_read_b128 v[196:199], v124 offset:7552
	v_add_f32_dpp v2, v2, v2 row_ror:4 row_mask:0xf bank_mask:0xf bound_ctrl:1
	ds_read_b128 v[200:203], v124 offset:7808
	ds_read_b128 v[204:207], v124 offset:8064
	ds_read_b32 v208, v110 offset:8320
	v_add_f32_dpp v2, v2, v2 row_ror:8 row_mask:0xf bank_mask:0xf bound_ctrl:1
	s_waitcnt lgkmcnt(6)
; #define LAS __attribute__((address_space(3)))
; __device__ __forceinline__ float row16_sum(float x) { x += dpp_mov<0xB1>(x); x += dpp_mov<0x4E>(x); x += dpp_mov<0x124>(x); x += dpp_mov<0x128>(x); return x; }
; __device__ __forceinline__ void up4(const u32x2 w, float (&f)[4]) { f[0] = bflo(w.x); f[1] = bfhi(w.x); f[2] = bflo(w.y); f[3] = bfhi(w.y); }
; __device__ __forceinline__ void scan_stage(const u32x2 (&pz)[8], LAS float* buf, float* RKB, size_t mrow0, int t0, int tid, int h, int half, ...
;     ...
;     up4(pz[0], zr); up4(pz[1], zk); up4(pz[2], zv); up4(pz[3], zrp); up4(pz[4], zkp); up4(pz[5], zvp); up4(pz[6], ew); up4(pz[7], ic);
;     f32x4 r, k2, v, kkv, w; float n2 = 0.f, rkb = 0.f;
; #pragma unroll
;     for (int e = 0; e < 4; ++e) { r[e] = zr[e] + (zrp[e] - zr[e]) * mu_r[e]; const float k = zk[e] + (zkp[e] - zk[e]) * mu_k[e]; v[e] = zv[e] + (zvp[e] - zv[e]) * mu_v[e];
; __device__ __forceinline__ void scan_phase(const KAS Args& a, LAS unsigned char* lds, int i, const int tid_, const int bid, const int nblk) {
;     ...
;                 for (int t = 0; t < TC; ++t) {
;                     f32x4 kk4n = kk4, nb4n = nb4, w4n = w4, k4n = k4, r4n = r4; float vn = v;
;                     if (t + 1 < TC) { const LAS float* sn = sb + (t + 1) * SST;
;                         kk4n = *(const LAS f32x4*)(sn); nb4n = *(const LAS f32x4*)(sn + 64); w4n = *(const LAS f32x4*)(sn + 128); k4n = *(const LAS f32x4*)(sn + 192); r4n = *(const LAS f32x4*)(sn + 256); vn = vb[(t + 1) * SST]; }
;                     __builtin_amdgcn_sched_barrier(0x6);
;                     float sa = fmaf(S[3], kk4[3], fmaf(S[2], kk4[2], fmaf(S[1], kk4[1], S[0] * kk4[0])));
;                     const f32x4 Tm = S * w4 + k4 * v;
;                     sa = row16_sum(sa);
;                     S = Tm + nb4 * sa;
;                     float y = fmaf(S[3], r4[3], fmaf(S[2], r4[2], fmaf(S[1], r4[1], S[0] * r4[0]))); y = row16_sum(y);
;                     ysel = (cgp == (t & 15)) ? y : ysel;
;                     if ((t & 15) == 15) yb[(t - 15 + cgp) * 32 + rl] = ysel;
;                     kk4 = kk4n; nb4 = nb4n; w4 = w4n; k4 = k4n; r4 = r4n; v = vn; }
	v_pk_fma_f32 v[36:37], v[140:141], v[2:3], v[40:41] op_sel_hi:[1,0,1]
	v_pk_fma_f32 v[38:39], v[142:143], v[2:3], v[42:43] op_sel_hi:[1,0,1]
	v_mul_f32_e32 v44, v36, v160
	v_mul_f32_e32 v49, v152, v36
	v_fmac_f32_e32 v44, v37, v161
	v_fmac_f32_e32 v49, v37, v153
	v_fmac_f32_e32 v44, v38, v162
	v_fmac_f32_e32 v49, v38, v154
	v_fmac_f32_e32 v44, v39, v163
	v_fmac_f32_e32 v49, v39, v155
	v_pk_mul_f32 v[40:41], v[172:173], v[158:159] op_sel_hi:[1,0]
	v_pk_mul_f32 v[42:43], v[174:175], v[158:159] op_sel_hi:[1,0]
	v_add_f32_dpp v2, v44, v44 quad_perm:[1,0,3,2] row_mask:0xf bank_mask:0xf bound_ctrl:1
	v_pk_fma_f32 v[40:41], v[36:37], v[168:169], v[40:41]
	v_pk_fma_f32 v[42:43], v[38:39], v[170:171], v[42:43]
	v_add_f32_dpp v2, v2, v2 quad_perm:[2,3,0,1] row_mask:0xf bank_mask:0xf bound_ctrl:1
	ds_read_b128 v[136:139], v124 offset:8448
	ds_read_b128 v[140:143], v124 offset:8704
	ds_read_b128 v[144:147], v124 offset:8960
	v_add_f32_dpp v2, v2, v2 row_ror:4 row_mask:0xf bank_mask:0xf bound_ctrl:1
	ds_read_b128 v[148:151], v124 offset:9216
	ds_read_b128 v[152:155], v124 offset:9472
	ds_read_b32 v156, v110 offset:9728
	v_add_f32_dpp v2, v2, v2 row_ror:8 row_mask:0xf bank_mask:0xf bound_ctrl:1
	v_cndmask_b32_e64 v56, v48, v49, s[8:9]
	v_cndmask_b32_e64 v57, v49, v48, s[8:9]
	s_waitcnt lgkmcnt(6)
	v_pk_fma_f32 v[36:37], v[164:165], v[2:3], v[40:41] op_sel_hi:[1,0,1]
	v_pk_fma_f32 v[38:39], v[166:167], v[2:3], v[42:43] op_sel_hi:[1,0,1]
	v_add_f32_dpp v50, v57, v56 quad_perm:[1,0,3,2] row_mask:0xf bank_mask:0xf bound_ctrl:1
	v_cndmask_b32_e64 v56, v47, v50, s[10:11]
	v_cndmask_b32_e64 v57, v50, v47, s[10:11]
	v_mul_f32_e32 v44, v36, v188
	v_mul_f32_e32 v52, v176, v36
	v_add_f32_dpp v51, v57, v56 quad_perm:[2,3,0,1] row_mask:0xf bank_mask:0xf bound_ctrl:1
	v_fmac_f32_e32 v44, v37, v189
	v_fmac_f32_e32 v52, v37, v177
	v_fmac_f32_e32 v44, v38, v190
	v_fmac_f32_e32 v52, v38, v178
	v_fmac_f32_e32 v44, v39, v191
	v_fmac_f32_e32 v52, v39, v179
	v_pk_mul_f32 v[40:41], v[200:201], v[208:209] op_sel_hi:[1,0]
	v_pk_mul_f32 v[42:43], v[202:203], v[208:209] op_sel_hi:[1,0]
	v_add_f32_dpp v2, v44, v44 quad_perm:[1,0,3,2] row_mask:0xf bank_mask:0xf bound_ctrl:1
	v_pk_fma_f32 v[40:41], v[36:37], v[196:197], v[40:41]
	v_pk_fma_f32 v[42:43], v[38:39], v[198:199], v[42:43]
	v_add_f32_dpp v2, v2, v2 quad_perm:[2,3,0,1] row_mask:0xf bank_mask:0xf bound_ctrl:1
	ds_read_b128 v[160:163], v124 offset:9856
	ds_read_b128 v[164:167], v124 offset:10112
	ds_read_b128 v[168:171], v124 offset:10368
	v_add_f32_dpp v2, v2, v2 row_ror:4 row_mask:0xf bank_mask:0xf bound_ctrl:1
	ds_read_b128 v[172:175], v124 offset:10624
	ds_read_b128 v[176:179], v124 offset:10880
	ds_read_b32 v158, v110 offset:11136
	v_add_f32_dpp v2, v2, v2 row_ror:8 row_mask:0xf bank_mask:0xf bound_ctrl:1
	s_waitcnt lgkmcnt(6)
	v_pk_fma_f32 v[36:37], v[192:193], v[2:3], v[40:41] op_sel_hi:[1,0,1]
	v_pk_fma_f32 v[38:39], v[194:195], v[2:3], v[42:43] op_sel_hi:[1,0,1]
	v_mul_f32_e32 v44, v36, v136
	v_mul_f32_e32 v53, v204, v36
	v_fmac_f32_e32 v44, v37, v137
	v_fmac_f32_e32 v53, v37, v205
	v_fmac_f32_e32 v44, v38, v138
	v_fmac_f32_e32 v53, v38, v206
	v_fmac_f32_e32 v44, v39, v139
	v_fmac_f32_e32 v53, v39, v207
	v_pk_mul_f32 v[40:41], v[148:149], v[156:157] op_sel_hi:[1,0]
	v_pk_mul_f32 v[42:43], v[150:151], v[156:157] op_sel_hi:[1,0]
	v_add_f32_dpp v2, v44, v44 quad_perm:[1,0,3,2] row_mask:0xf bank_mask:0xf bound_ctrl:1
	v_pk_fma_f32 v[40:41], v[36:37], v[144:145], v[40:41]
	v_pk_fma_f32 v[42:43], v[38:39], v[146:147], v[42:43]
	v_add_f32_dpp v2, v2, v2 quad_perm:[2,3,0,1] row_mask:0xf bank_mask:0xf bound_ctrl:1
	s_waitcnt vmcnt(4)
	v_lshlrev_b32_e32 v28, 16, v80
	ds_read_b128 v[188:191], v124 offset:11264
	ds_read_b128 v[192:195], v124 offset:11520
	ds_read_b128 v[196:199], v124 offset:11776
	v_add_f32_dpp v2, v2, v2 row_ror:4 row_mask:0xf bank_mask:0xf bound_ctrl:1
	ds_read_b128 v[200:203], v124 offset:12032
	ds_read_b128 v[204:207], v124 offset:12288
	ds_read_b32 v208, v110 offset:12544
	v_add_f32_dpp v2, v2, v2 row_ror:8 row_mask:0xf bank_mask:0xf bound_ctrl:1
	v_cndmask_b32_e64 v56, v52, v53, s[8:9]
	v_cndmask_b32_e64 v57, v53, v52, s[8:9]
	v_and_b32_e32 v29, 0xffff0000, v80
	v_lshlrev_b32_e32 v30, 16, v86
	s_waitcnt lgkmcnt(6)
	v_pk_fma_f32 v[36:37], v[140:141], v[2:3], v[40:41] op_sel_hi:[1,0,1]
	v_pk_fma_f32 v[38:39], v[142:143], v[2:3], v[42:43] op_sel_hi:[1,0,1]
	v_add_f32_dpp v54, v57, v56 quad_perm:[1,0,3,2] row_mask:0xf bank_mask:0xf bound_ctrl:1
	v_mul_f32_e32 v44, v36, v160
	v_mul_f32_e32 v55, v152, v36
	v_fmac_f32_e32 v44, v37, v161
	v_fmac_f32_e32 v55, v37, v153
	v_fmac_f32_e32 v44, v38, v162
	v_fmac_f32_e32 v55, v38, v154
	v_fmac_f32_e32 v44, v39, v163
	v_fmac_f32_e32 v55, v39, v155
	v_pk_mul_f32 v[40:41], v[172:173], v[158:159] op_sel_hi:[1,0]
	v_pk_mul_f32 v[42:43], v[174:175], v[158:159] op_sel_hi:[1,0]
	v_add_f32_dpp v2, v44, v44 quad_perm:[1,0,3,2] row_mask:0xf bank_mask:0xf bound_ctrl:1
	v_pk_fma_f32 v[40:41], v[36:37], v[168:169], v[40:41]
	v_pk_fma_f32 v[42:43], v[38:39], v[170:171], v[42:43]
	v_add_f32_dpp v2, v2, v2 quad_perm:[2,3,0,1] row_mask:0xf bank_mask:0xf bound_ctrl:1
	v_and_b32_e32 v31, 0xffff0000, v86
	v_pk_add_f32 v[30:31], v[30:31], v[28:29] neg_lo:[0,1] neg_hi:[0,1]
	ds_read_b128 v[136:139], v124 offset:12672
	ds_read_b128 v[140:143], v124 offset:12928
	ds_read_b128 v[144:147], v124 offset:13184
	v_add_f32_dpp v2, v2, v2 row_ror:4 row_mask:0xf bank_mask:0xf bound_ctrl:1
	ds_read_b128 v[148:151], v124 offset:13440
	ds_read_b128 v[152:155], v124 offset:13696
	ds_read_b32 v156, v110 offset:13952
	v_add_f32_dpp v2, v2, v2 row_ror:8 row_mask:0xf bank_mask:0xf bound_ctrl:1
	s_waitcnt vmcnt(3)
; #define LAS __attribute__((address_space(3)))
; __device__ __forceinline__ float row16_sum(float x) { x += dpp_mov<0xB1>(x); x += dpp_mov<0x4E>(x); x += dpp_mov<0x124>(x); x += dpp_mov<0x128>(x); return x; }
; __device__ __forceinline__ void up4(const u32x2 w, float (&f)[4]) { f[0] = bflo(w.x); f[1] = bfhi(w.x); f[2] = bflo(w.y); f[3] = bfhi(w.y); }
; __device__ __forceinline__ void scan_stage(const u32x2 (&pz)[8], LAS float* buf, float* RKB, size_t mrow0, int t0, int tid, int h, int half, ...
;     ...
;     up4(pz[0], zr); up4(pz[1], zk); up4(pz[2], zv); up4(pz[3], zrp); up4(pz[4], zkp); up4(pz[5], zvp); up4(pz[6], ew); up4(pz[7], ic);
;     f32x4 r, k2, v, kkv, w; float n2 = 0.f, rkb = 0.f;
; #pragma unroll
;     for (int e = 0; e < 4; ++e) { r[e] = zr[e] + (zrp[e] - zr[e]) * mu_r[e]; const float k = zk[e] + (zkp[e] - zk[e]) * mu_k[e]; v[e] = zv[e] + (zvp[e] - zv[e]) * mu_v[e];
;         kkv[e] = k * kkc[e]; n2 += kkv[e] * kkv[e]; k2[e] = k * (1.0f + (ic[e] - 1.0f) * kac[e]); w[e] = __builtin_amdgcn_exp2f(-1.4426950408889634f * ew[e]); rkb += r[e] * k2[e] * rkc[e]; }
; __device__ __forceinline__ void scan_phase(const KAS Args& a, LAS unsigned char* lds, int i, const int tid_, const int bid, const int nblk) {
;     ...
;                 for (int t = 0; t < TC; ++t) {
;                     f32x4 kk4n = kk4, nb4n = nb4, w4n = w4, k4n = k4, r4n = r4; float vn = v;
;                     if (t + 1 < TC) { const LAS float* sn = sb + (t + 1) * SST;
;                         kk4n = *(const LAS f32x4*)(sn); nb4n = *(const LAS f32x4*)(sn + 64); w4n = *(const LAS f32x4*)(sn + 128); k4n = *(const LAS f32x4*)(sn + 192); r4n = *(const LAS f32x4*)(sn + 256); vn = vb[(t + 1) * SST]; }
;                     __builtin_amdgcn_sched_barrier(0x6);
;                     float sa = fmaf(S[3], kk4[3], fmaf(S[2], kk4[2], fmaf(S[1], kk4[1], S[0] * kk4[0])));
;                     const f32x4 Tm = S * w4 + k4 * v;
;                     sa = row16_sum(sa);
;                     S = Tm + nb4 * sa;
;                     float y = fmaf(S[3], r4[3], fmaf(S[2], r4[2], fmaf(S[1], r4[1], S[0] * r4[0]))); y = row16_sum(y);
;                     ysel = (cgp == (t & 15)) ? y : ysel;
;                     if ((t & 15) == 15) yb[(t - 15 + cgp) * 32 + rl] = ysel;
;                     kk4 = kk4n; nb4 = nb4n; w4 = w4n; k4 = k4n; r4 = r4n; v = vn; }
	v_lshlrev_b32_e32 v32, 16, v88
	s_waitcnt lgkmcnt(6)
	v_pk_fma_f32 v[36:37], v[164:165], v[2:3], v[40:41] op_sel_hi:[1,0,1]
	v_pk_fma_f32 v[38:39], v[166:167], v[2:3], v[42:43] op_sel_hi:[1,0,1]
	v_mul_f32_e32 v44, v36, v188
	v_mul_f32_e32 v58, v176, v36
	v_fmac_f32_e32 v44, v37, v189
	v_fmac_f32_e32 v58, v37, v177
	v_fmac_f32_e32 v44, v38, v190
	v_fmac_f32_e32 v58, v38, v178
	v_fmac_f32_e32 v44, v39, v191
	v_fmac_f32_e32 v58, v39, v179
	v_pk_mul_f32 v[40:41], v[200:201], v[208:209] op_sel_hi:[1,0]
	v_pk_mul_f32 v[42:43], v[202:203], v[208:209] op_sel_hi:[1,0]
	v_add_f32_dpp v2, v44, v44 quad_perm:[1,0,3,2] row_mask:0xf bank_mask:0xf bound_ctrl:1
	v_pk_fma_f32 v[40:41], v[36:37], v[196:197], v[40:41]
	v_pk_fma_f32 v[42:43], v[38:39], v[198:199], v[42:43]
	v_add_f32_dpp v2, v2, v2 quad_perm:[2,3,0,1] row_mask:0xf bank_mask:0xf bound_ctrl:1
	v_pk_fma_f32 v[28:29], v[16:17], v[30:31], v[28:29]
	v_lshlrev_b32_e32 v30, 16, v82
	ds_read_b128 v[160:163], v124 offset:14080
	ds_read_b128 v[164:167], v124 offset:14336
	ds_read_b128 v[168:171], v124 offset:14592
	v_add_f32_dpp v2, v2, v2 row_ror:4 row_mask:0xf bank_mask:0xf bound_ctrl:1
	ds_read_b128 v[172:175], v124 offset:14848
	ds_read_b128 v[176:179], v124 offset:15104
	ds_read_b32 v158, v110 offset:15360
	v_add_f32_dpp v2, v2, v2 row_ror:8 row_mask:0xf bank_mask:0xf bound_ctrl:1
	v_cndmask_b32_e64 v56, v55, v58, s[8:9]
	v_cndmask_b32_e64 v57, v58, v55, s[8:9]
	v_and_b32_e32 v31, 0xffff0000, v82
	v_and_b32_e32 v33, 0xffff0000, v88
	s_waitcnt lgkmcnt(6)
	v_pk_fma_f32 v[36:37], v[192:193], v[2:3], v[40:41] op_sel_hi:[1,0,1]
	v_pk_fma_f32 v[38:39], v[194:195], v[2:3], v[42:43] op_sel_hi:[1,0,1]
	v_add_f32_dpp v59, v57, v56 quad_perm:[1,0,3,2] row_mask:0xf bank_mask:0xf bound_ctrl:1
	v_cndmask_b32_e64 v56, v54, v59, s[10:11]
	v_cndmask_b32_e64 v57, v59, v54, s[10:11]
	v_mul_f32_e32 v44, v36, v136
	v_mul_f32_e32 v62, v204, v36
	v_add_f32_dpp v60, v57, v56 quad_perm:[2,3,0,1] row_mask:0xf bank_mask:0xf bound_ctrl:1
	v_fmac_f32_e32 v44, v37, v137
	v_fmac_f32_e32 v62, v37, v205
	v_cndmask_b32_e64 v56, v51, v60, s[12:13]
	v_fmac_f32_e32 v44, v38, v138
	v_fmac_f32_e32 v62, v38, v206
	v_cndmask_b32_e64 v57, v60, v51, s[12:13]
	v_fmac_f32_e32 v44, v39, v139
	v_fmac_f32_e32 v62, v39, v207
	v_pk_mul_f32 v[40:41], v[148:149], v[156:157] op_sel_hi:[1,0]
	v_pk_mul_f32 v[42:43], v[150:151], v[156:157] op_sel_hi:[1,0]
	v_add_f32_dpp v2, v44, v44 quad_perm:[1,0,3,2] row_mask:0xf bank_mask:0xf bound_ctrl:1
	v_pk_fma_f32 v[40:41], v[36:37], v[144:145], v[40:41]
	v_pk_fma_f32 v[42:43], v[38:39], v[146:147], v[42:43]
	v_add_f32_dpp v2, v2, v2 quad_perm:[2,3,0,1] row_mask:0xf bank_mask:0xf bound_ctrl:1
	s_waitcnt vmcnt(0)
	v_lshlrev_b32_e32 v210, 16, v94
	ds_read_b128 v[188:191], v124 offset:15488
	ds_read_b128 v[192:195], v124 offset:15744
	ds_read_b128 v[196:199], v124 offset:16000
	v_add_f32_dpp v2, v2, v2 row_ror:4 row_mask:0xf bank_mask:0xf bound_ctrl:1
	ds_read_b128 v[200:203], v124 offset:16256
	ds_read_b128 v[204:207], v124 offset:16512
	ds_read_b32 v208, v110 offset:16768
	v_add_f32_dpp v2, v2, v2 row_ror:8 row_mask:0xf bank_mask:0xf bound_ctrl:1
	v_add_f32_dpp v61, v57, v56 row_shl:4 row_mask:0xf bank_mask:0x5
	v_and_b32_e32 v211, 0xffff0000, v94
	v_pk_add_f32 v[32:33], v[32:33], v[30:31] neg_lo:[0,1] neg_hi:[0,1]
	s_waitcnt lgkmcnt(6)
	v_pk_fma_f32 v[36:37], v[140:141], v[2:3], v[40:41] op_sel_hi:[1,0,1]
	v_pk_fma_f32 v[38:39], v[142:143], v[2:3], v[42:43] op_sel_hi:[1,0,1]
	v_add_f32_dpp v61, v57, v56 row_shr:4 row_mask:0xf bank_mask:0xa
	v_mul_f32_e32 v44, v36, v160
	v_mul_f32_e32 v63, v152, v36
	v_fmac_f32_e32 v44, v37, v161
	v_fmac_f32_e32 v63, v37, v153
	v_fmac_f32_e32 v44, v38, v162
	v_fmac_f32_e32 v63, v38, v154
	v_fmac_f32_e32 v44, v39, v163
	v_fmac_f32_e32 v63, v39, v155
	v_pk_mul_f32 v[40:41], v[172:173], v[158:159] op_sel_hi:[1,0]
	v_pk_mul_f32 v[42:43], v[174:175], v[158:159] op_sel_hi:[1,0]
	v_add_f32_dpp v2, v44, v44 quad_perm:[1,0,3,2] row_mask:0xf bank_mask:0xf bound_ctrl:1
	v_pk_fma_f32 v[40:41], v[36:37], v[168:169], v[40:41]
	v_pk_fma_f32 v[42:43], v[38:39], v[170:171], v[42:43]
	v_add_f32_dpp v2, v2, v2 quad_perm:[2,3,0,1] row_mask:0xf bank_mask:0xf bound_ctrl:1
	v_lshlrev_b32_e32 v216, 16, v89
	v_pk_fma_f32 v[30:31], v[20:21], v[32:33], v[30:31]
	ds_read_b128 v[136:139], v124 offset:16896
	ds_read_b128 v[140:143], v124 offset:17152
	ds_read_b128 v[144:147], v124 offset:17408
	v_add_f32_dpp v2, v2, v2 row_ror:4 row_mask:0xf bank_mask:0xf bound_ctrl:1
	ds_read_b128 v[148:151], v124 offset:17664
	ds_read_b128 v[152:155], v124 offset:17920
	ds_read_b32 v156, v110 offset:18176
	v_add_f32_dpp v2, v2, v2 row_ror:8 row_mask:0xf bank_mask:0xf bound_ctrl:1
	v_cndmask_b32_e64 v56, v62, v63, s[8:9]
	v_cndmask_b32_e64 v57, v63, v62, s[8:9]
	v_pk_add_f32 v[32:33], v[210:211], -1.0 op_sel_hi:[1,0]
	v_pk_mul_f32 v[212:213], v[12:13], v[30:31]
	s_waitcnt lgkmcnt(6)
	v_pk_fma_f32 v[36:37], v[164:165], v[2:3], v[40:41] op_sel_hi:[1,0,1]
	v_pk_fma_f32 v[38:39], v[166:167], v[2:3], v[42:43] op_sel_hi:[1,0,1]
	v_add_f32_dpp v64, v57, v56 quad_perm:[1,0,3,2] row_mask:0xf bank_mask:0xf bound_ctrl:1
	v_mul_f32_e32 v44, v36, v188
	v_mul_f32_e32 v65, v176, v36
	v_fmac_f32_e32 v44, v37, v189
	v_fmac_f32_e32 v65, v37, v177
	v_fmac_f32_e32 v44, v38, v190
	v_fmac_f32_e32 v65, v38, v178
	v_fmac_f32_e32 v44, v39, v191
	v_fmac_f32_e32 v65, v39, v179
	v_pk_mul_f32 v[40:41], v[200:201], v[208:209] op_sel_hi:[1,0]
	v_pk_mul_f32 v[42:43], v[202:203], v[208:209] op_sel_hi:[1,0]
	v_add_f32_dpp v2, v44, v44 quad_perm:[1,0,3,2] row_mask:0xf bank_mask:0xf bound_ctrl:1
	v_pk_fma_f32 v[40:41], v[36:37], v[196:197], v[40:41]
	v_pk_fma_f32 v[42:43], v[38:39], v[198:199], v[42:43]
	v_add_f32_dpp v2, v2, v2 quad_perm:[2,3,0,1] row_mask:0xf bank_mask:0xf bound_ctrl:1
	v_pk_fma_f32 v[32:33], v[24:25], v[32:33], 1.0 op_sel_hi:[1,1,0]
	v_and_b32_e32 v217, 0xffff0000, v89
	ds_read_b128 v[160:163], v124 offset:18304
	ds_read_b128 v[164:167], v124 offset:18560
	ds_read_b128 v[168:171], v124 offset:18816
	v_add_f32_dpp v2, v2, v2 row_ror:4 row_mask:0xf bank_mask:0xf bound_ctrl:1
	ds_read_b128 v[172:175], v124 offset:19072
	ds_read_b128 v[176:179], v124 offset:19328
	ds_read_b32 v158, v110 offset:19584
	v_add_f32_dpp v2, v2, v2 row_ror:8 row_mask:0xf bank_mask:0xf bound_ctrl:1
	v_pk_mul_f32 v[32:33], v[30:31], v[32:33]
	v_lshlrev_b32_e32 v30, 16, v81
	s_waitcnt lgkmcnt(6)
; #define LAS __attribute__((address_space(3)))
; __device__ __forceinline__ float row16_sum(float x) { x += dpp_mov<0xB1>(x); x += dpp_mov<0x4E>(x); x += dpp_mov<0x124>(x); x += dpp_mov<0x128>(x); return x; }
; __device__ __forceinline__ void scan_stage(const u32x2 (&pz)[8], LAS float* buf, float* RKB, size_t mrow0, int t0, int tid, int h, int half, ...
;     ...
;     for (int e = 0; e < 4; ++e) { r[e] = zr[e] + (zrp[e] - zr[e]) * mu_r[e]; const float k = zk[e] + (zkp[e] - zk[e]) * mu_k[e]; v[e] = zv[e] + (zvp[e] - zv[e]) * mu_v[e];
;         kkv[e] = k * kkc[e]; n2 += kkv[e] * kkv[e]; k2[e] = k * (1.0f + (ic[e] - 1.0f) * kac[e]); w[e] = __builtin_amdgcn_exp2f(-1.4426950408889634f * ew[e]); rkb += r[e] * k2[e] * rkc[e]; }
;     n2 = row16_sum(n2); rkb = row16_sum(rkb);
; __device__ __forceinline__ void scan_phase(const KAS Args& a, LAS unsigned char* lds, int i, const int tid_, const int bid, const int nblk) {
;     ...
;                 for (int t = 0; t < TC; ++t) {
;                     f32x4 kk4n = kk4, nb4n = nb4, w4n = w4, k4n = k4, r4n = r4; float vn = v;
;                     if (t + 1 < TC) { const LAS float* sn = sb + (t + 1) * SST;
;                         kk4n = *(const LAS f32x4*)(sn); nb4n = *(const LAS f32x4*)(sn + 64); w4n = *(const LAS f32x4*)(sn + 128); k4n = *(const LAS f32x4*)(sn + 192); r4n = *(const LAS f32x4*)(sn + 256); vn = vb[(t + 1) * SST]; }
;                     __builtin_amdgcn_sched_barrier(0x6);
;                     float sa = fmaf(S[3], kk4[3], fmaf(S[2], kk4[2], fmaf(S[1], kk4[1], S[0] * kk4[0])));
;                     const f32x4 Tm = S * w4 + k4 * v;
;                     sa = row16_sum(sa);
;                     S = Tm + nb4 * sa;
;                     float y = fmaf(S[3], r4[3], fmaf(S[2], r4[2], fmaf(S[1], r4[1], S[0] * r4[0]))); y = row16_sum(y);
;                     ysel = (cgp == (t & 15)) ? y : ysel;
;                     if ((t & 15) == 15) yb[(t - 15 + cgp) * 32 + rl] = ysel;
;                     kk4 = kk4n; nb4 = nb4n; w4 = w4n; k4 = k4n; r4 = r4n; v = vn; }
	v_pk_fma_f32 v[36:37], v[192:193], v[2:3], v[40:41] op_sel_hi:[1,0,1]
	v_pk_fma_f32 v[38:39], v[194:195], v[2:3], v[42:43] op_sel_hi:[1,0,1]
	v_mul_f32_e32 v44, v36, v136
	v_mul_f32_e32 v66, v204, v36
	v_fmac_f32_e32 v44, v37, v137
	v_fmac_f32_e32 v66, v37, v205
	v_fmac_f32_e32 v44, v38, v138
	v_fmac_f32_e32 v66, v38, v206
	v_fmac_f32_e32 v44, v39, v139
	v_fmac_f32_e32 v66, v39, v207
	v_pk_mul_f32 v[40:41], v[148:149], v[156:157] op_sel_hi:[1,0]
	v_pk_mul_f32 v[42:43], v[150:151], v[156:157] op_sel_hi:[1,0]
	v_add_f32_dpp v2, v44, v44 quad_perm:[1,0,3,2] row_mask:0xf bank_mask:0xf bound_ctrl:1
	v_pk_fma_f32 v[40:41], v[36:37], v[144:145], v[40:41]
	v_pk_fma_f32 v[42:43], v[38:39], v[146:147], v[42:43]
	v_add_f32_dpp v2, v2, v2 quad_perm:[2,3,0,1] row_mask:0xf bank_mask:0xf bound_ctrl:1
	v_pk_mul_f32 v[34:35], v[28:29], v[32:33]
	v_and_b32_e32 v31, 0xffff0000, v81
	ds_read_b128 v[188:191], v124 offset:19712
	ds_read_b128 v[192:195], v124 offset:19968
	ds_read_b128 v[196:199], v124 offset:20224
	v_add_f32_dpp v2, v2, v2 row_ror:4 row_mask:0xf bank_mask:0xf bound_ctrl:1
	ds_read_b128 v[200:203], v124 offset:20480
	ds_read_b128 v[204:207], v124 offset:20736
	ds_read_b32 v208, v110 offset:20992
	v_add_f32_dpp v2, v2, v2 row_ror:8 row_mask:0xf bank_mask:0xf bound_ctrl:1
	v_cndmask_b32_e64 v56, v65, v66, s[8:9]
	v_cndmask_b32_e64 v57, v66, v65, s[8:9]
	v_fma_f32 v224, v4, v34, 0
	v_fmac_f32_e32 v224, v5, v35
	s_waitcnt lgkmcnt(6)
	v_pk_fma_f32 v[36:37], v[140:141], v[2:3], v[40:41] op_sel_hi:[1,0,1]
	v_pk_fma_f32 v[38:39], v[142:143], v[2:3], v[42:43] op_sel_hi:[1,0,1]
	v_add_f32_dpp v67, v57, v56 quad_perm:[1,0,3,2] row_mask:0xf bank_mask:0xf bound_ctrl:1
	v_cndmask_b32_e64 v56, v64, v67, s[10:11]
	v_cndmask_b32_e64 v57, v67, v64, s[10:11]
	v_mul_f32_e32 v44, v36, v160
	v_mul_f32_e32 v46, v152, v36
	v_add_f32_dpp v45, v57, v56 quad_perm:[2,3,0,1] row_mask:0xf bank_mask:0xf bound_ctrl:1
	v_fmac_f32_e32 v44, v37, v161
	v_fmac_f32_e32 v46, v37, v153
	v_fmac_f32_e32 v44, v38, v162
	v_fmac_f32_e32 v46, v38, v154
	v_fmac_f32_e32 v44, v39, v163
	v_fmac_f32_e32 v46, v39, v155
	v_pk_mul_f32 v[40:41], v[172:173], v[158:159] op_sel_hi:[1,0]
	v_pk_mul_f32 v[42:43], v[174:175], v[158:159] op_sel_hi:[1,0]
	v_add_f32_dpp v2, v44, v44 quad_perm:[1,0,3,2] row_mask:0xf bank_mask:0xf bound_ctrl:1
	v_pk_fma_f32 v[40:41], v[36:37], v[168:169], v[40:41]
	v_pk_fma_f32 v[42:43], v[38:39], v[170:171], v[42:43]
	v_add_f32_dpp v2, v2, v2 quad_perm:[2,3,0,1] row_mask:0xf bank_mask:0xf bound_ctrl:1
	v_lshlrev_b32_e32 v34, 16, v87
	v_and_b32_e32 v35, 0xffff0000, v87
	ds_read_b128 v[136:139], v124 offset:21120
	ds_read_b128 v[140:143], v124 offset:21376
	ds_read_b128 v[144:147], v124 offset:21632
	v_add_f32_dpp v2, v2, v2 row_ror:4 row_mask:0xf bank_mask:0xf bound_ctrl:1
	ds_read_b128 v[148:151], v124 offset:21888
	ds_read_b128 v[152:155], v124 offset:22144
	ds_read_b32 v156, v110 offset:22400
	v_add_f32_dpp v2, v2, v2 row_ror:8 row_mask:0xf bank_mask:0xf bound_ctrl:1
	v_pk_add_f32 v[34:35], v[34:35], v[30:31] neg_lo:[0,1] neg_hi:[0,1]
	v_lshlrev_b32_e32 v214, 16, v95
	s_waitcnt lgkmcnt(6)
	v_pk_fma_f32 v[36:37], v[164:165], v[2:3], v[40:41] op_sel_hi:[1,0,1]
	v_pk_fma_f32 v[38:39], v[166:167], v[2:3], v[42:43] op_sel_hi:[1,0,1]
	v_mul_f32_e32 v44, v36, v188
	v_mul_f32_e32 v48, v176, v36
	v_fmac_f32_e32 v44, v37, v189
	v_fmac_f32_e32 v48, v37, v177
	v_fmac_f32_e32 v44, v38, v190
	v_fmac_f32_e32 v48, v38, v178
	v_fmac_f32_e32 v44, v39, v191
	v_fmac_f32_e32 v48, v39, v179
	v_pk_mul_f32 v[40:41], v[200:201], v[208:209] op_sel_hi:[1,0]
	v_pk_mul_f32 v[42:43], v[202:203], v[208:209] op_sel_hi:[1,0]
	v_add_f32_dpp v2, v44, v44 quad_perm:[1,0,3,2] row_mask:0xf bank_mask:0xf bound_ctrl:1
	v_pk_fma_f32 v[40:41], v[36:37], v[196:197], v[40:41]
	v_pk_fma_f32 v[42:43], v[38:39], v[198:199], v[42:43]
	v_add_f32_dpp v2, v2, v2 quad_perm:[2,3,0,1] row_mask:0xf bank_mask:0xf bound_ctrl:1
	v_pk_fma_f32 v[30:31], v[18:19], v[34:35], v[30:31]
	v_lshlrev_b32_e32 v34, 16, v83
	ds_read_b128 v[160:163], v124 offset:22528
	ds_read_b128 v[164:167], v124 offset:22784
	ds_read_b128 v[168:171], v124 offset:23040
	v_add_f32_dpp v2, v2, v2 row_ror:4 row_mask:0xf bank_mask:0xf bound_ctrl:1
	ds_read_b128 v[172:175], v124 offset:23296
	ds_read_b128 v[176:179], v124 offset:23552
	ds_read_b32 v158, v110 offset:23808
	v_add_f32_dpp v2, v2, v2 row_ror:8 row_mask:0xf bank_mask:0xf bound_ctrl:1
	v_cndmask_b32_e64 v56, v46, v48, s[8:9]
	v_cndmask_b32_e64 v57, v48, v46, s[8:9]
	v_and_b32_e32 v35, 0xffff0000, v83
	v_and_b32_e32 v215, 0xffff0000, v95
	s_waitcnt lgkmcnt(6)
	v_pk_fma_f32 v[36:37], v[192:193], v[2:3], v[40:41] op_sel_hi:[1,0,1]
	v_pk_fma_f32 v[38:39], v[194:195], v[2:3], v[42:43] op_sel_hi:[1,0,1]
	v_add_f32_dpp v49, v57, v56 quad_perm:[1,0,3,2] row_mask:0xf bank_mask:0xf bound_ctrl:1
	v_mul_f32_e32 v44, v36, v136
	v_mul_f32_e32 v47, v204, v36
	v_fmac_f32_e32 v44, v37, v137
	v_fmac_f32_e32 v47, v37, v205
	v_fmac_f32_e32 v44, v38, v138
	v_fmac_f32_e32 v47, v38, v206
	v_fmac_f32_e32 v44, v39, v139
	v_fmac_f32_e32 v47, v39, v207
	v_pk_mul_f32 v[40:41], v[148:149], v[156:157] op_sel_hi:[1,0]
	v_pk_mul_f32 v[42:43], v[150:151], v[156:157] op_sel_hi:[1,0]
	v_add_f32_dpp v2, v44, v44 quad_perm:[1,0,3,2] row_mask:0xf bank_mask:0xf bound_ctrl:1
	v_pk_fma_f32 v[40:41], v[36:37], v[144:145], v[40:41]
	v_pk_fma_f32 v[42:43], v[38:39], v[146:147], v[42:43]
	v_add_f32_dpp v2, v2, v2 quad_perm:[2,3,0,1] row_mask:0xf bank_mask:0xf bound_ctrl:1
	v_pk_add_f32 v[216:217], v[216:217], v[34:35] neg_lo:[0,1] neg_hi:[0,1]
	v_pk_mul_f32 v[218:219], v[212:213], v[212:213]
	ds_read_b128 v[188:191], v124 offset:23936
	ds_read_b128 v[192:195], v124 offset:24192
	ds_read_b128 v[196:199], v124 offset:24448
	v_add_f32_dpp v2, v2, v2 row_ror:4 row_mask:0xf bank_mask:0xf bound_ctrl:1
	ds_read_b128 v[200:203], v124 offset:24704
	ds_read_b128 v[204:207], v124 offset:24960
	ds_read_b32 v208, v110 offset:25216
	v_add_f32_dpp v2, v2, v2 row_ror:8 row_mask:0xf bank_mask:0xf bound_ctrl:1
	v_pk_fma_f32 v[216:217], v[22:23], v[216:217], v[34:35]
	v_pk_add_f32 v[34:35], v[214:215], -1.0 op_sel_hi:[1,0]
	s_waitcnt lgkmcnt(6)
; #define LAS __attribute__((address_space(3)))
; __device__ __forceinline__ float row16_sum(float x) { x += dpp_mov<0xB1>(x); x += dpp_mov<0x4E>(x); x += dpp_mov<0x124>(x); x += dpp_mov<0x128>(x); return x; }
; __device__ __forceinline__ void scan_stage(const u32x2 (&pz)[8], LAS float* buf, float* RKB, size_t mrow0, int t0, int tid, int h, int half, ...
;     ...
;     for (int e = 0; e < 4; ++e) { r[e] = zr[e] + (zrp[e] - zr[e]) * mu_r[e]; const float k = zk[e] + (zkp[e] - zk[e]) * mu_k[e]; v[e] = zv[e] + (zvp[e] - zv[e]) * mu_v[e];
;         kkv[e] = k * kkc[e]; n2 += kkv[e] * kkv[e]; k2[e] = k * (1.0f + (ic[e] - 1.0f) * kac[e]); w[e] = __builtin_amdgcn_exp2f(-1.4426950408889634f * ew[e]); rkb += r[e] * k2[e] * rkc[e]; }
;     n2 = row16_sum(n2); rkb = row16_sum(rkb);
; __device__ __forceinline__ void scan_phase(const KAS Args& a, LAS unsigned char* lds, int i, const int tid_, const int bid, const int nblk) {
;     ...
;                 for (int t = 0; t < TC; ++t) {
;                     f32x4 kk4n = kk4, nb4n = nb4, w4n = w4, k4n = k4, r4n = r4; float vn = v;
;                     if (t + 1 < TC) { const LAS float* sn = sb + (t + 1) * SST;
;                         kk4n = *(const LAS f32x4*)(sn); nb4n = *(const LAS f32x4*)(sn + 64); w4n = *(const LAS f32x4*)(sn + 128); k4n = *(const LAS f32x4*)(sn + 192); r4n = *(const LAS f32x4*)(sn + 256); vn = vb[(t + 1) * SST]; }
;                     __builtin_amdgcn_sched_barrier(0x6);
;                     float sa = fmaf(S[3], kk4[3], fmaf(S[2], kk4[2], fmaf(S[1], kk4[1], S[0] * kk4[0])));
;                     const f32x4 Tm = S * w4 + k4 * v;
;                     sa = row16_sum(sa);
;                     S = Tm + nb4 * sa;
;                     float y = fmaf(S[3], r4[3], fmaf(S[2], r4[2], fmaf(S[1], r4[1], S[0] * r4[0]))); y = row16_sum(y);
;                     ysel = (cgp == (t & 15)) ? y : ysel;
;                     if ((t & 15) == 15) yb[(t - 15 + cgp) * 32 + rl] = ysel;
;                     kk4 = kk4n; nb4 = nb4n; w4 = w4n; k4 = k4n; r4 = r4n; v = vn; }
	v_pk_fma_f32 v[36:37], v[140:141], v[2:3], v[40:41] op_sel_hi:[1,0,1]
	v_pk_fma_f32 v[38:39], v[142:143], v[2:3], v[42:43] op_sel_hi:[1,0,1]
	v_mul_f32_e32 v44, v36, v160
	v_mul_f32_e32 v50, v152, v36
	v_fmac_f32_e32 v44, v37, v161
	v_fmac_f32_e32 v50, v37, v153
	v_fmac_f32_e32 v44, v38, v162
	v_fmac_f32_e32 v50, v38, v154
	v_fmac_f32_e32 v44, v39, v163
	v_fmac_f32_e32 v50, v39, v155
	v_pk_mul_f32 v[40:41], v[172:173], v[158:159] op_sel_hi:[1,0]
	v_pk_mul_f32 v[42:43], v[174:175], v[158:159] op_sel_hi:[1,0]
	v_add_f32_dpp v2, v44, v44 quad_perm:[1,0,3,2] row_mask:0xf bank_mask:0xf bound_ctrl:1
	v_pk_fma_f32 v[40:41], v[36:37], v[168:169], v[40:41]
	v_pk_fma_f32 v[42:43], v[38:39], v[170:171], v[42:43]
	v_add_f32_dpp v2, v2, v2 quad_perm:[2,3,0,1] row_mask:0xf bank_mask:0xf bound_ctrl:1
	v_add_f32_e32 v228, v218, v219
	v_pk_fma_f32 v[34:35], v[26:27], v[34:35], 1.0 op_sel_hi:[1,1,0]
	ds_read_b128 v[136:139], v124 offset:25344
	ds_read_b128 v[140:143], v124 offset:25600
	ds_read_b128 v[144:147], v124 offset:25856
	v_add_f32_dpp v2, v2, v2 row_ror:4 row_mask:0xf bank_mask:0xf bound_ctrl:1
	ds_read_b128 v[148:151], v124 offset:26112
	ds_read_b128 v[152:155], v124 offset:26368
	ds_read_b32 v156, v110 offset:26624
	v_add_f32_dpp v2, v2, v2 row_ror:8 row_mask:0xf bank_mask:0xf bound_ctrl:1
	v_cndmask_b32_e64 v56, v47, v50, s[8:9]
	v_cndmask_b32_e64 v57, v50, v47, s[8:9]
	v_mov_b32_e32 v218, 0
	v_pk_mul_f32 v[34:35], v[216:217], v[34:35]
	v_add_f32_dpp v52, v57, v56 quad_perm:[1,0,3,2] row_mask:0xf bank_mask:0xf bound_ctrl:1
	v_cndmask_b32_e64 v56, v49, v52, s[10:11]
	v_cndmask_b32_e64 v57, v52, v49, s[10:11]
	s_nop 0
	s_nop 0
	v_add_f32_dpp v53, v57, v56 quad_perm:[2,3,0,1] row_mask:0xf bank_mask:0xf bound_ctrl:1
	v_cndmask_b32_e64 v56, v45, v53, s[12:13]
	v_cndmask_b32_e64 v57, v53, v45, s[12:13]
	s_nop 0
	s_nop 0
	v_add_f32_dpp v55, v57, v56 row_shl:4 row_mask:0xf bank_mask:0x5
	s_nop 0
	s_nop 0
	v_add_f32_dpp v55, v57, v56 row_shr:4 row_mask:0xf bank_mask:0xa
	v_cndmask_b32_e64 v56, v61, v55, s[14:15]
	v_cndmask_b32_e64 v57, v55, v61, s[14:15]
	s_nop 0
	s_nop 0
	v_add_f32_dpp v58, v57, v56 row_ror:8 row_mask:0xf bank_mask:0xf bound_ctrl:1
	ds_write_b32 v122, v58
	s_waitcnt lgkmcnt(7)
	v_pk_fma_f32 v[36:37], v[164:165], v[2:3], v[40:41] op_sel_hi:[1,0,1]
	v_pk_fma_f32 v[38:39], v[166:167], v[2:3], v[42:43] op_sel_hi:[1,0,1]
	v_mul_f32_e32 v44, v36, v188
	v_mul_f32_e32 v54, v176, v36
	v_fmac_f32_e32 v44, v37, v189
	v_fmac_f32_e32 v54, v37, v177
	v_fmac_f32_e32 v44, v38, v190
	v_fmac_f32_e32 v54, v38, v178
	v_fmac_f32_e32 v44, v39, v191
	v_fmac_f32_e32 v54, v39, v179
	v_pk_mul_f32 v[40:41], v[200:201], v[208:209] op_sel_hi:[1,0]
	v_pk_mul_f32 v[42:43], v[202:203], v[208:209] op_sel_hi:[1,0]
	v_add_f32_dpp v2, v44, v44 quad_perm:[1,0,3,2] row_mask:0xf bank_mask:0xf bound_ctrl:1
	v_pk_fma_f32 v[40:41], v[36:37], v[196:197], v[40:41]
	v_pk_fma_f32 v[42:43], v[38:39], v[198:199], v[42:43]
	v_add_f32_dpp v2, v2, v2 quad_perm:[2,3,0,1] row_mask:0xf bank_mask:0xf bound_ctrl:1
	v_pk_mul_f32 v[216:217], v[14:15], v[216:217]
	v_pk_mul_f32 v[220:221], v[30:31], v[34:35]
	ds_read_b128 v[160:163], v124 offset:26752
	ds_read_b128 v[164:167], v124 offset:27008
	ds_read_b128 v[168:171], v124 offset:27264
	v_add_f32_dpp v2, v2, v2 row_ror:4 row_mask:0xf bank_mask:0xf bound_ctrl:1
	ds_read_b128 v[172:175], v124 offset:27520
	ds_read_b128 v[176:179], v124 offset:27776
	ds_read_b32 v158, v110 offset:28032
	v_add_f32_dpp v2, v2, v2 row_ror:8 row_mask:0xf bank_mask:0xf bound_ctrl:1
	v_pk_mul_f32 v[222:223], v[216:217], v[216:217]
	v_fmac_f32_e32 v224, v6, v220
	s_waitcnt lgkmcnt(7)
	v_pk_fma_f32 v[36:37], v[192:193], v[2:3], v[40:41] op_sel_hi:[1,0,1]
	v_pk_fma_f32 v[38:39], v[194:195], v[2:3], v[42:43] op_sel_hi:[1,0,1]
	v_mul_f32_e32 v44, v36, v136
	v_mul_f32_e32 v59, v204, v36
	v_fmac_f32_e32 v44, v37, v137
	v_fmac_f32_e32 v59, v37, v205
	v_fmac_f32_e32 v44, v38, v138
	v_fmac_f32_e32 v59, v38, v206
	v_fmac_f32_e32 v44, v39, v139
	v_fmac_f32_e32 v59, v39, v207
	v_pk_mul_f32 v[40:41], v[148:149], v[156:157] op_sel_hi:[1,0]
	v_pk_mul_f32 v[42:43], v[150:151], v[156:157] op_sel_hi:[1,0]
	v_add_f32_dpp v2, v44, v44 quad_perm:[1,0,3,2] row_mask:0xf bank_mask:0xf bound_ctrl:1
	v_pk_fma_f32 v[40:41], v[36:37], v[144:145], v[40:41]
	v_pk_fma_f32 v[42:43], v[38:39], v[146:147], v[42:43]
	v_add_f32_dpp v2, v2, v2 quad_perm:[2,3,0,1] row_mask:0xf bank_mask:0xf bound_ctrl:1
	v_add_f32_e32 v228, v222, v228
	v_add_f32_e32 v228, v223, v228
	ds_read_b128 v[188:191], v124 offset:28160
	ds_read_b128 v[192:195], v124 offset:28416
	ds_read_b128 v[196:199], v124 offset:28672
	v_add_f32_dpp v2, v2, v2 row_ror:4 row_mask:0xf bank_mask:0xf bound_ctrl:1
	ds_read_b128 v[200:203], v124 offset:28928
	ds_read_b128 v[204:207], v124 offset:29184
	ds_read_b32 v208, v110 offset:29440
	v_add_f32_dpp v2, v2, v2 row_ror:8 row_mask:0xf bank_mask:0xf bound_ctrl:1
	v_cndmask_b32_e64 v56, v54, v59, s[8:9]
	v_cndmask_b32_e64 v57, v59, v54, s[8:9]
	v_fmac_f32_e32 v224, v7, v221
	v_mov_b32_e32 v220, 0
	s_waitcnt lgkmcnt(6)
; #define LAS __attribute__((address_space(3)))
; __device__ __forceinline__ float row16_sum(float x) { x += dpp_mov<0xB1>(x); x += dpp_mov<0x4E>(x); x += dpp_mov<0x124>(x); x += dpp_mov<0x128>(x); return x; }
; __device__ __forceinline__ void scan_stage(const u32x2 (&pz)[8], LAS float* buf, float* RKB, size_t mrow0, int t0, int tid, int h, int half, ...
;     ...
;     n2 = row16_sum(n2); rkb = row16_sum(rkb);
;     const float inv = __builtin_amdgcn_rsqf(fmaxf(n2, 1e-24f));
; __device__ __forceinline__ void scan_phase(const KAS Args& a, LAS unsigned char* lds, int i, const int tid_, const int bid, const int nblk) {
;     ...
;                 for (int t = 0; t < TC; ++t) {
;                     f32x4 kk4n = kk4, nb4n = nb4, w4n = w4, k4n = k4, r4n = r4; float vn = v;
;                     if (t + 1 < TC) { const LAS float* sn = sb + (t + 1) * SST;
;                         kk4n = *(const LAS f32x4*)(sn); nb4n = *(const LAS f32x4*)(sn + 64); w4n = *(const LAS f32x4*)(sn + 128); k4n = *(const LAS f32x4*)(sn + 192); r4n = *(const LAS f32x4*)(sn + 256); vn = vb[(t + 1) * SST]; }
;                     __builtin_amdgcn_sched_barrier(0x6);
;                     float sa = fmaf(S[3], kk4[3], fmaf(S[2], kk4[2], fmaf(S[1], kk4[1], S[0] * kk4[0])));
;                     const f32x4 Tm = S * w4 + k4 * v;
;                     sa = row16_sum(sa);
;                     S = Tm + nb4 * sa;
;                     float y = fmaf(S[3], r4[3], fmaf(S[2], r4[2], fmaf(S[1], r4[1], S[0] * r4[0]))); y = row16_sum(y);
;                     ysel = (cgp == (t & 15)) ? y : ysel;
;                     if ((t & 15) == 15) yb[(t - 15 + cgp) * 32 + rl] = ysel;
;                     kk4 = kk4n; nb4 = nb4n; w4 = w4n; k4 = k4n; r4 = r4n; v = vn; }
	v_pk_fma_f32 v[36:37], v[140:141], v[2:3], v[40:41] op_sel_hi:[1,0,1]
	v_pk_fma_f32 v[38:39], v[142:143], v[2:3], v[42:43] op_sel_hi:[1,0,1]
	v_add_f32_dpp v51, v57, v56 quad_perm:[1,0,3,2] row_mask:0xf bank_mask:0xf bound_ctrl:1
	v_mul_f32_e32 v44, v36, v160
	v_mul_f32_e32 v60, v152, v36
	v_fmac_f32_e32 v44, v37, v161
	v_fmac_f32_e32 v60, v37, v153
	v_fmac_f32_e32 v44, v38, v162
	v_fmac_f32_e32 v60, v38, v154
	v_fmac_f32_e32 v44, v39, v163
	v_fmac_f32_e32 v60, v39, v155
	v_pk_mul_f32 v[40:41], v[172:173], v[158:159] op_sel_hi:[1,0]
	v_pk_mul_f32 v[42:43], v[174:175], v[158:159] op_sel_hi:[1,0]
	v_add_f32_dpp v2, v44, v44 quad_perm:[1,0,3,2] row_mask:0xf bank_mask:0xf bound_ctrl:1
	v_pk_fma_f32 v[40:41], v[36:37], v[168:169], v[40:41]
	v_pk_fma_f32 v[42:43], v[38:39], v[170:171], v[42:43]
	v_add_f32_dpp v2, v2, v2 quad_perm:[2,3,0,1] row_mask:0xf bank_mask:0xf bound_ctrl:1
	v_add_f32_dpp v228, v228, v228 quad_perm:[1,0,3,2] row_mask:0xf bank_mask:0xf bound_ctrl:1
	v_add_f32_dpp v219, v224, v224 quad_perm:[1,0,3,2] row_mask:0xf bank_mask:0xf bound_ctrl:1
	ds_read_b128 v[136:139], v124 offset:29568
	ds_read_b128 v[140:143], v124 offset:29824
	ds_read_b128 v[144:147], v124 offset:30080
	v_add_f32_dpp v2, v2, v2 row_ror:4 row_mask:0xf bank_mask:0xf bound_ctrl:1
	ds_read_b128 v[148:151], v124 offset:30336
	ds_read_b128 v[152:155], v124 offset:30592
	ds_read_b32 v156, v110 offset:30848
	v_add_f32_dpp v2, v2, v2 row_ror:8 row_mask:0xf bank_mask:0xf bound_ctrl:1
	v_add_f32_dpp v228, v228, v228 quad_perm:[2,3,0,1] row_mask:0xf bank_mask:0xf bound_ctrl:1
	v_add_f32_dpp v219, v219, v219 quad_perm:[2,3,0,1] row_mask:0xf bank_mask:0xf bound_ctrl:1
	s_waitcnt lgkmcnt(6)
	v_pk_fma_f32 v[36:37], v[164:165], v[2:3], v[40:41] op_sel_hi:[1,0,1]
	v_pk_fma_f32 v[38:39], v[166:167], v[2:3], v[42:43] op_sel_hi:[1,0,1]
	v_mul_f32_e32 v44, v36, v188
	v_mul_f32_e32 v62, v176, v36
	v_fmac_f32_e32 v44, v37, v189
	v_fmac_f32_e32 v62, v37, v177
	v_fmac_f32_e32 v44, v38, v190
	v_fmac_f32_e32 v62, v38, v178
	v_fmac_f32_e32 v44, v39, v191
	v_fmac_f32_e32 v62, v39, v179
	v_pk_mul_f32 v[40:41], v[200:201], v[208:209] op_sel_hi:[1,0]
	v_pk_mul_f32 v[42:43], v[202:203], v[208:209] op_sel_hi:[1,0]
	v_add_f32_dpp v2, v44, v44 quad_perm:[1,0,3,2] row_mask:0xf bank_mask:0xf bound_ctrl:1
	v_pk_fma_f32 v[40:41], v[36:37], v[196:197], v[40:41]
	v_pk_fma_f32 v[42:43], v[38:39], v[198:199], v[42:43]
	v_add_f32_dpp v2, v2, v2 quad_perm:[2,3,0,1] row_mask:0xf bank_mask:0xf bound_ctrl:1
	v_add_f32_dpp v228, v228, v228 row_ror:4 row_mask:0xf bank_mask:0xf bound_ctrl:1
	v_add_f32_dpp v219, v219, v219 row_ror:4 row_mask:0xf bank_mask:0xf bound_ctrl:1
	ds_read_b128 v[160:163], v124 offset:30976
	ds_read_b128 v[164:167], v124 offset:31232
	ds_read_b128 v[168:171], v124 offset:31488
	v_add_f32_dpp v2, v2, v2 row_ror:4 row_mask:0xf bank_mask:0xf bound_ctrl:1
	ds_read_b128 v[172:175], v124 offset:31744
	ds_read_b128 v[176:179], v124 offset:32000
	ds_read_b32 v158, v110 offset:32256
	v_add_f32_dpp v2, v2, v2 row_ror:8 row_mask:0xf bank_mask:0xf bound_ctrl:1
	v_cndmask_b32_e64 v56, v60, v62, s[8:9]
	v_cndmask_b32_e64 v57, v62, v60, s[8:9]
	v_mov_b32_dpp v218, v228 row_ror:8 row_mask:0xf bank_mask:0xf
	v_mov_b32_dpp v220, v219 row_ror:8 row_mask:0xf bank_mask:0xf
	s_waitcnt lgkmcnt(6)
	v_pk_fma_f32 v[36:37], v[192:193], v[2:3], v[40:41] op_sel_hi:[1,0,1]
	v_pk_fma_f32 v[38:39], v[194:195], v[2:3], v[42:43] op_sel_hi:[1,0,1]
	v_add_f32_dpp v63, v57, v56 quad_perm:[1,0,3,2] row_mask:0xf bank_mask:0xf bound_ctrl:1
	v_cndmask_b32_e64 v56, v51, v63, s[10:11]
	v_cndmask_b32_e64 v57, v63, v51, s[10:11]
	v_mul_f32_e32 v44, v36, v136
	v_mul_f32_e32 v66, v204, v36
	v_add_f32_dpp v65, v57, v56 quad_perm:[2,3,0,1] row_mask:0xf bank_mask:0xf bound_ctrl:1
	v_fmac_f32_e32 v44, v37, v137
	v_fmac_f32_e32 v66, v37, v205
	v_fmac_f32_e32 v44, v38, v138
	v_fmac_f32_e32 v66, v38, v206
	v_fmac_f32_e32 v44, v39, v139
	v_fmac_f32_e32 v66, v39, v207
	v_pk_mul_f32 v[40:41], v[148:149], v[156:157] op_sel_hi:[1,0]
	v_pk_mul_f32 v[42:43], v[150:151], v[156:157] op_sel_hi:[1,0]
	v_add_f32_dpp v2, v44, v44 quad_perm:[1,0,3,2] row_mask:0xf bank_mask:0xf bound_ctrl:1
	v_pk_fma_f32 v[40:41], v[36:37], v[144:145], v[40:41]
	v_pk_fma_f32 v[42:43], v[38:39], v[146:147], v[42:43]
	v_add_f32_dpp v2, v2, v2 quad_perm:[2,3,0,1] row_mask:0xf bank_mask:0xf bound_ctrl:1
	v_add_f32_e32 v245, v219, v220
	v_add_f32_e32 v228, v228, v218
	ds_read_b128 v[188:191], v124 offset:32384
	ds_read_b128 v[192:195], v124 offset:32640
	ds_read_b128 v[196:199], v124 offset:32896
	v_add_f32_dpp v2, v2, v2 row_ror:4 row_mask:0xf bank_mask:0xf bound_ctrl:1
	ds_read_b128 v[200:203], v124 offset:33152
	ds_read_b128 v[204:207], v124 offset:33408
	ds_read_b32 v208, v110 offset:33664
	v_add_f32_dpp v2, v2, v2 row_ror:8 row_mask:0xf bank_mask:0xf bound_ctrl:1
	v_max_f32_e32 v228, 0x179abe15, v228
	v_lshlrev_b32_e32 v219, 16, v92
	s_waitcnt lgkmcnt(6)
; #define LAS __attribute__((address_space(3)))
; __device__ __forceinline__ float row16_sum(float x) { x += dpp_mov<0xB1>(x); x += dpp_mov<0x4E>(x); x += dpp_mov<0x124>(x); x += dpp_mov<0x128>(x); return x; }
; __device__ __forceinline__ void scan_stage(const u32x2 (&pz)[8], LAS float* buf, float* RKB, size_t mrow0, int t0, int tid, int h, int half, ...
;     ...
;         kkv[e] = k * kkc[e]; n2 += kkv[e] * kkv[e]; k2[e] = k * (1.0f + (ic[e] - 1.0f) * kac[e]); w[e] = __builtin_amdgcn_exp2f(-1.4426950408889634f * ew[e]); rkb += r[e] * k2[e] * rkc[e]; }
;     n2 = row16_sum(n2); rkb = row16_sum(rkb);
;     const float inv = __builtin_amdgcn_rsqf(fmaxf(n2, 1e-24f));
;     const f32x4 kkn = kkv * inv; f32x4 nb;
; #pragma unroll
;     for (int e = 0; e < 4; ++e) nb[e] = -kkn[e] * ic[e];
; __device__ __forceinline__ void scan_phase(const KAS Args& a, LAS unsigned char* lds, int i, const int tid_, const int bid, const int nblk) {
;     ...
;                 for (int t = 0; t < TC; ++t) {
;                     f32x4 kk4n = kk4, nb4n = nb4, w4n = w4, k4n = k4, r4n = r4; float vn = v;
;                     if (t + 1 < TC) { const LAS float* sn = sb + (t + 1) * SST;
;                         kk4n = *(const LAS f32x4*)(sn); nb4n = *(const LAS f32x4*)(sn + 64); w4n = *(const LAS f32x4*)(sn + 128); k4n = *(const LAS f32x4*)(sn + 192); r4n = *(const LAS f32x4*)(sn + 256); vn = vb[(t + 1) * SST]; }
;                     __builtin_amdgcn_sched_barrier(0x6);
;                     float sa = fmaf(S[3], kk4[3], fmaf(S[2], kk4[2], fmaf(S[1], kk4[1], S[0] * kk4[0])));
;                     const f32x4 Tm = S * w4 + k4 * v;
;                     sa = row16_sum(sa);
;                     S = Tm + nb4 * sa;
;                     float y = fmaf(S[3], r4[3], fmaf(S[2], r4[2], fmaf(S[1], r4[1], S[0] * r4[0]))); y = row16_sum(y);
;                     ysel = (cgp == (t & 15)) ? y : ysel;
;                     if ((t & 15) == 15) yb[(t - 15 + cgp) * 32 + rl] = ysel;
;                     kk4 = kk4n; nb4 = nb4n; w4 = w4n; k4 = k4n; r4 = r4n; v = vn; }
	v_pk_fma_f32 v[36:37], v[140:141], v[2:3], v[40:41] op_sel_hi:[1,0,1]
	v_pk_fma_f32 v[38:39], v[142:143], v[2:3], v[42:43] op_sel_hi:[1,0,1]
	v_mul_f32_e32 v44, v36, v160
	v_mul_f32_e32 v64, v152, v36
	v_fmac_f32_e32 v44, v37, v161
	v_fmac_f32_e32 v64, v37, v153
	v_fmac_f32_e32 v44, v38, v162
	v_fmac_f32_e32 v64, v38, v154
	v_fmac_f32_e32 v44, v39, v163
	v_fmac_f32_e32 v64, v39, v155
	v_pk_mul_f32 v[40:41], v[172:173], v[158:159] op_sel_hi:[1,0]
	v_pk_mul_f32 v[42:43], v[174:175], v[158:159] op_sel_hi:[1,0]
	v_add_f32_dpp v2, v44, v44 quad_perm:[1,0,3,2] row_mask:0xf bank_mask:0xf bound_ctrl:1
	v_pk_fma_f32 v[40:41], v[36:37], v[168:169], v[40:41]
	v_pk_fma_f32 v[42:43], v[38:39], v[170:171], v[42:43]
	v_add_f32_dpp v2, v2, v2 quad_perm:[2,3,0,1] row_mask:0xf bank_mask:0xf bound_ctrl:1
	v_rsq_f32_e32 v228, v228
	v_and_b32_e32 v221, 0xffff0000, v92
	ds_read_b128 v[136:139], v124 offset:33792
	ds_read_b128 v[140:143], v124 offset:34048
	ds_read_b128 v[144:147], v124 offset:34304
	v_add_f32_dpp v2, v2, v2 row_ror:4 row_mask:0xf bank_mask:0xf bound_ctrl:1
	ds_read_b128 v[148:151], v124 offset:34560
	ds_read_b128 v[152:155], v124 offset:34816
	ds_read_b32 v156, v110 offset:35072
	v_add_f32_dpp v2, v2, v2 row_ror:8 row_mask:0xf bank_mask:0xf bound_ctrl:1
	v_cndmask_b32_e64 v56, v66, v64, s[8:9]
	v_cndmask_b32_e64 v57, v64, v66, s[8:9]
	v_mul_f32_e32 v219, 0xbfb8aa3b, v219
	s_bitcmp1_b32 s62, 0
	s_cselect_b32 s2, 0xb000, 0
	s_waitcnt lgkmcnt(6)
	v_pk_fma_f32 v[36:37], v[164:165], v[2:3], v[40:41] op_sel_hi:[1,0,1]
	v_pk_fma_f32 v[38:39], v[166:167], v[2:3], v[42:43] op_sel_hi:[1,0,1]
	v_add_f32_dpp v67, v57, v56 quad_perm:[1,0,3,2] row_mask:0xf bank_mask:0xf bound_ctrl:1
	v_mul_f32_e32 v44, v36, v188
	v_mul_f32_e32 v46, v176, v36
	v_fmac_f32_e32 v44, v37, v189
	v_fmac_f32_e32 v46, v37, v177
	v_fmac_f32_e32 v44, v38, v190
	v_fmac_f32_e32 v46, v38, v178
	v_fmac_f32_e32 v44, v39, v191
	v_fmac_f32_e32 v46, v39, v179
	v_pk_mul_f32 v[40:41], v[200:201], v[208:209] op_sel_hi:[1,0]
	v_pk_mul_f32 v[42:43], v[202:203], v[208:209] op_sel_hi:[1,0]
	v_add_f32_dpp v2, v44, v44 quad_perm:[1,0,3,2] row_mask:0xf bank_mask:0xf bound_ctrl:1
	v_pk_fma_f32 v[40:41], v[36:37], v[196:197], v[40:41]
	v_pk_fma_f32 v[42:43], v[38:39], v[198:199], v[42:43]
	v_add_f32_dpp v2, v2, v2 quad_perm:[2,3,0,1] row_mask:0xf bank_mask:0xf bound_ctrl:1
	v_lshlrev_b32_e32 v222, 16, v93
	v_and_b32_e32 v223, 0xffff0000, v93
	ds_read_b128 v[160:163], v124 offset:35200
	ds_read_b128 v[164:167], v124 offset:35456
	ds_read_b128 v[168:171], v124 offset:35712
	v_add_f32_dpp v2, v2, v2 row_ror:4 row_mask:0xf bank_mask:0xf bound_ctrl:1
	ds_read_b128 v[172:175], v124 offset:35968
	ds_read_b128 v[176:179], v124 offset:36224
	ds_read_b32 v158, v110 offset:36480
	v_add_f32_dpp v2, v2, v2 row_ror:8 row_mask:0xf bank_mask:0xf bound_ctrl:1
	v_exp_f32_e32 v220, v219
	v_mul_f32_e32 v219, 0xbfb8aa3b, v221
	s_waitcnt lgkmcnt(6)
	v_pk_fma_f32 v[36:37], v[192:193], v[2:3], v[40:41] op_sel_hi:[1,0,1]
	v_pk_fma_f32 v[38:39], v[194:195], v[2:3], v[42:43] op_sel_hi:[1,0,1]
	v_mul_f32_e32 v44, v36, v136
	v_mul_f32_e32 v48, v204, v36
	v_fmac_f32_e32 v44, v37, v137
	v_fmac_f32_e32 v48, v37, v205
	v_fmac_f32_e32 v44, v38, v138
	v_fmac_f32_e32 v48, v38, v206
	v_fmac_f32_e32 v44, v39, v139
	v_fmac_f32_e32 v48, v39, v207
	v_pk_mul_f32 v[40:41], v[148:149], v[156:157] op_sel_hi:[1,0]
	v_pk_mul_f32 v[42:43], v[150:151], v[156:157] op_sel_hi:[1,0]
	v_add_f32_dpp v2, v44, v44 quad_perm:[1,0,3,2] row_mask:0xf bank_mask:0xf bound_ctrl:1
	v_pk_fma_f32 v[40:41], v[36:37], v[144:145], v[40:41]
	v_pk_fma_f32 v[42:43], v[38:39], v[146:147], v[42:43]
	v_add_f32_dpp v2, v2, v2 quad_perm:[2,3,0,1] row_mask:0xf bank_mask:0xf bound_ctrl:1
	v_exp_f32_e32 v221, v219
	v_mul_f32_e32 v219, 0xbfb8aa3b, v222
	ds_read_b128 v[188:191], v124 offset:36608
	ds_read_b128 v[192:195], v124 offset:36864
	ds_read_b128 v[196:199], v124 offset:37120
	v_add_f32_dpp v2, v2, v2 row_ror:4 row_mask:0xf bank_mask:0xf bound_ctrl:1
	ds_read_b128 v[200:203], v124 offset:37376
	ds_read_b128 v[204:207], v124 offset:37632
	ds_read_b32 v208, v110 offset:37888
	v_add_f32_dpp v2, v2, v2 row_ror:8 row_mask:0xf bank_mask:0xf bound_ctrl:1
	v_cndmask_b32_e64 v56, v46, v48, s[8:9]
	v_cndmask_b32_e64 v57, v48, v46, s[8:9]
	v_mul_f32_e32 v218, 0xbfb8aa3b, v223
	v_exp_f32_e32 v222, v219
	s_waitcnt lgkmcnt(6)
	v_pk_fma_f32 v[36:37], v[140:141], v[2:3], v[40:41] op_sel_hi:[1,0,1]
	v_pk_fma_f32 v[38:39], v[142:143], v[2:3], v[42:43] op_sel_hi:[1,0,1]
	v_add_f32_dpp v47, v57, v56 quad_perm:[1,0,3,2] row_mask:0xf bank_mask:0xf bound_ctrl:1
	v_cndmask_b32_e64 v56, v67, v47, s[10:11]
	v_cndmask_b32_e64 v57, v47, v67, s[10:11]
	v_mul_f32_e32 v44, v36, v160
	v_mul_f32_e32 v52, v152, v36
	v_add_f32_dpp v50, v57, v56 quad_perm:[2,3,0,1] row_mask:0xf bank_mask:0xf bound_ctrl:1
	v_fmac_f32_e32 v44, v37, v161
	v_fmac_f32_e32 v52, v37, v153
	v_cndmask_b32_e64 v56, v65, v50, s[12:13]
	v_fmac_f32_e32 v44, v38, v162
	v_fmac_f32_e32 v52, v38, v154
	v_cndmask_b32_e64 v57, v50, v65, s[12:13]
	v_fmac_f32_e32 v44, v39, v163
	v_fmac_f32_e32 v52, v39, v155
	v_pk_mul_f32 v[40:41], v[172:173], v[158:159] op_sel_hi:[1,0]
	v_pk_mul_f32 v[42:43], v[174:175], v[158:159] op_sel_hi:[1,0]
	v_add_f32_dpp v2, v44, v44 quad_perm:[1,0,3,2] row_mask:0xf bank_mask:0xf bound_ctrl:1
	v_pk_fma_f32 v[40:41], v[36:37], v[168:169], v[40:41]
	v_pk_fma_f32 v[42:43], v[38:39], v[170:171], v[42:43]
	v_add_f32_dpp v2, v2, v2 quad_perm:[2,3,0,1] row_mask:0xf bank_mask:0xf bound_ctrl:1
	v_exp_f32_e32 v223, v218
	v_pk_mul_f32 v[224:225], v[212:213], v[228:229] op_sel_hi:[1,0]
	ds_read_b128 v[136:139], v124 offset:38016
	ds_read_b128 v[140:143], v124 offset:38272
	ds_read_b128 v[144:147], v124 offset:38528
	v_add_f32_dpp v2, v2, v2 row_ror:4 row_mask:0xf bank_mask:0xf bound_ctrl:1
	ds_read_b128 v[148:151], v124 offset:38784
	ds_read_b128 v[152:155], v124 offset:39040
	ds_read_b32 v156, v110 offset:39296
	v_add_f32_dpp v2, v2, v2 row_ror:8 row_mask:0xf bank_mask:0xf bound_ctrl:1
	v_add_f32_dpp v49, v57, v56 row_shl:4 row_mask:0xf bank_mask:0x5
	v_pk_mul_f32 v[226:227], v[216:217], v[228:229] op_sel_hi:[1,0]
	v_add_u32_e32 v228, s2, v113
	s_waitcnt lgkmcnt(6)
; #define LAS __attribute__((address_space(3)))
; __device__ __forceinline__ float row16_sum(float x) { x += dpp_mov<0xB1>(x); x += dpp_mov<0x4E>(x); x += dpp_mov<0x124>(x); x += dpp_mov<0x128>(x); return x; }
; __device__ __forceinline__ void scan_stage(const u32x2 (&pz)[8], LAS float* buf, float* RKB, size_t mrow0, int t0, int tid, int h, int half, ...
;     ...
;     const float inv = __builtin_amdgcn_rsqf(fmaxf(n2, 1e-24f));
;     const f32x4 kkn = kkv * inv; f32x4 nb;
; #pragma unroll
;     for (int e = 0; e < 4; ++e) nb[e] = -kkn[e] * ic[e];
;     if (half == 0 && cgp == 0) RKB[(mrow0 + t0 + tl) * 8 + h] = rkb;
;     LAS float* sb = buf + tl * SST + 4 * cgp;
;     *(LAS f32x4*)(sb) = kkn; *(LAS f32x4*)(sb + 64) = nb; *(LAS f32x4*)(sb + 128) = w; *(LAS f32x4*)(sb + 192) = k2; *(LAS f32x4*)(sb + 256) = r;
; __device__ __forceinline__ void scan_phase(const KAS Args& a, LAS unsigned char* lds, int i, const int tid_, const int bid, const int nblk) {
;     ...
;                 for (int t = 0; t < TC; ++t) {
;                     f32x4 kk4n = kk4, nb4n = nb4, w4n = w4, k4n = k4, r4n = r4; float vn = v;
;                     if (t + 1 < TC) { const LAS float* sn = sb + (t + 1) * SST;
;                         kk4n = *(const LAS f32x4*)(sn); nb4n = *(const LAS f32x4*)(sn + 64); w4n = *(const LAS f32x4*)(sn + 128); k4n = *(const LAS f32x4*)(sn + 192); r4n = *(const LAS f32x4*)(sn + 256); vn = vb[(t + 1) * SST]; }
;                     __builtin_amdgcn_sched_barrier(0x6);
;                     float sa = fmaf(S[3], kk4[3], fmaf(S[2], kk4[2], fmaf(S[1], kk4[1], S[0] * kk4[0])));
;                     const f32x4 Tm = S * w4 + k4 * v;
;                     sa = row16_sum(sa);
;                     S = Tm + nb4 * sa;
;                     float y = fmaf(S[3], r4[3], fmaf(S[2], r4[2], fmaf(S[1], r4[1], S[0] * r4[0]))); y = row16_sum(y);
;                     ysel = (cgp == (t & 15)) ? y : ysel;
;                     if ((t & 15) == 15) yb[(t - 15 + cgp) * 32 + rl] = ysel;
;                     kk4 = kk4n; nb4 = nb4n; w4 = w4n; k4 = k4n; r4 = r4n; v = vn; }
	v_pk_fma_f32 v[36:37], v[164:165], v[2:3], v[40:41] op_sel_hi:[1,0,1]
	v_pk_fma_f32 v[38:39], v[166:167], v[2:3], v[42:43] op_sel_hi:[1,0,1]
	v_add_f32_dpp v49, v57, v56 row_shr:4 row_mask:0xf bank_mask:0xa
	v_mul_f32_e32 v44, v36, v188
	v_mul_f32_e32 v45, v176, v36
	v_fmac_f32_e32 v44, v37, v189
	v_fmac_f32_e32 v45, v37, v177
	v_fmac_f32_e32 v44, v38, v190
	v_fmac_f32_e32 v45, v38, v178
	v_fmac_f32_e32 v44, v39, v191
	v_fmac_f32_e32 v45, v39, v179
	v_pk_mul_f32 v[40:41], v[200:201], v[208:209] op_sel_hi:[1,0]
	v_pk_mul_f32 v[42:43], v[202:203], v[208:209] op_sel_hi:[1,0]
	v_add_f32_dpp v2, v44, v44 quad_perm:[1,0,3,2] row_mask:0xf bank_mask:0xf bound_ctrl:1
	v_pk_fma_f32 v[40:41], v[36:37], v[196:197], v[40:41]
	v_pk_fma_f32 v[42:43], v[38:39], v[198:199], v[42:43]
	v_add_f32_dpp v2, v2, v2 quad_perm:[2,3,0,1] row_mask:0xf bank_mask:0xf bound_ctrl:1
	v_pk_mul_f32 v[212:213], v[214:215], v[226:227] neg_lo:[0,1] neg_hi:[0,1]
	v_add_u32_e32 v214, v228, v114
	ds_read_b128 v[160:163], v124 offset:39424
	ds_read_b128 v[164:167], v124 offset:39680
	ds_read_b128 v[168:171], v124 offset:39936
	v_add_f32_dpp v2, v2, v2 row_ror:4 row_mask:0xf bank_mask:0xf bound_ctrl:1
	ds_read_b128 v[172:175], v124 offset:40192
	ds_read_b128 v[176:179], v124 offset:40448
	ds_read_b32 v158, v110 offset:40704
	v_add_f32_dpp v2, v2, v2 row_ror:8 row_mask:0xf bank_mask:0xf bound_ctrl:1
	v_cndmask_b32_e64 v56, v52, v45, s[8:9]
	v_cndmask_b32_e64 v57, v45, v52, s[8:9]
	v_pk_mul_f32 v[210:211], v[210:211], v[224:225] neg_lo:[0,1] neg_hi:[0,1]
	ds_write_b128 v214, v[224:227]
	s_waitcnt lgkmcnt(7)
	v_pk_fma_f32 v[36:37], v[192:193], v[2:3], v[40:41] op_sel_hi:[1,0,1]
	v_pk_fma_f32 v[38:39], v[194:195], v[2:3], v[42:43] op_sel_hi:[1,0,1]
	v_add_f32_dpp v53, v57, v56 quad_perm:[1,0,3,2] row_mask:0xf bank_mask:0xf bound_ctrl:1
	v_mul_f32_e32 v44, v36, v136
	v_mul_f32_e32 v61, v204, v36
	v_fmac_f32_e32 v44, v37, v137
	v_fmac_f32_e32 v61, v37, v205
	v_fmac_f32_e32 v44, v38, v138
	v_fmac_f32_e32 v61, v38, v206
	v_fmac_f32_e32 v44, v39, v139
	v_fmac_f32_e32 v61, v39, v207
	v_pk_mul_f32 v[40:41], v[148:149], v[156:157] op_sel_hi:[1,0]
	v_pk_mul_f32 v[42:43], v[150:151], v[156:157] op_sel_hi:[1,0]
	v_add_f32_dpp v2, v44, v44 quad_perm:[1,0,3,2] row_mask:0xf bank_mask:0xf bound_ctrl:1
	v_pk_fma_f32 v[40:41], v[36:37], v[144:145], v[40:41]
	v_pk_fma_f32 v[42:43], v[38:39], v[146:147], v[42:43]
	v_add_f32_dpp v2, v2, v2 quad_perm:[2,3,0,1] row_mask:0xf bank_mask:0xf bound_ctrl:1
	ds_write_b128 v214, v[210:213] offset:256
	ds_write_b128 v214, v[220:223] offset:512
	ds_read_b128 v[188:191], v124 offset:40832
	ds_read_b128 v[192:195], v124 offset:41088
	ds_read_b128 v[196:199], v124 offset:41344
	v_add_f32_dpp v2, v2, v2 row_ror:4 row_mask:0xf bank_mask:0xf bound_ctrl:1
	ds_read_b128 v[200:203], v124 offset:41600
	ds_read_b128 v[204:207], v124 offset:41856
	ds_read_b32 v208, v110 offset:42112
	v_add_f32_dpp v2, v2, v2 row_ror:8 row_mask:0xf bank_mask:0xf bound_ctrl:1
	ds_write_b128 v214, v[32:35] offset:768
	ds_write_b128 v214, v[28:31] offset:1024
	s_waitcnt lgkmcnt(11)
	v_pk_fma_f32 v[36:37], v[140:141], v[2:3], v[40:41] op_sel_hi:[1,0,1]
	v_pk_fma_f32 v[38:39], v[142:143], v[2:3], v[42:43] op_sel_hi:[1,0,1]
	v_mul_f32_e32 v44, v36, v160
	v_mul_f32_e32 v55, v152, v36
	v_fmac_f32_e32 v44, v37, v161
	v_fmac_f32_e32 v55, v37, v153
	v_fmac_f32_e32 v44, v38, v162
	v_fmac_f32_e32 v55, v38, v154
	v_fmac_f32_e32 v44, v39, v163
	v_fmac_f32_e32 v55, v39, v155
	v_pk_mul_f32 v[40:41], v[172:173], v[158:159] op_sel_hi:[1,0]
	v_pk_mul_f32 v[42:43], v[174:175], v[158:159] op_sel_hi:[1,0]
	v_add_f32_dpp v2, v44, v44 quad_perm:[1,0,3,2] row_mask:0xf bank_mask:0xf bound_ctrl:1
	v_pk_fma_f32 v[40:41], v[36:37], v[168:169], v[40:41]
	v_pk_fma_f32 v[42:43], v[38:39], v[170:171], v[42:43]
	v_add_f32_dpp v2, v2, v2 quad_perm:[2,3,0,1] row_mask:0xf bank_mask:0xf bound_ctrl:1
	ds_read_b128 v[136:139], v124 offset:42240
	ds_read_b128 v[140:143], v124 offset:42496
	ds_read_b128 v[144:147], v124 offset:42752
	v_add_f32_dpp v2, v2, v2 row_ror:4 row_mask:0xf bank_mask:0xf bound_ctrl:1
	ds_read_b128 v[148:151], v124 offset:43008
	ds_read_b128 v[152:155], v124 offset:43264
	ds_read_b32 v156, v110 offset:43520
	v_add_f32_dpp v2, v2, v2 row_ror:8 row_mask:0xf bank_mask:0xf bound_ctrl:1
	v_cndmask_b32_e64 v56, v61, v55, s[8:9]
	v_cndmask_b32_e64 v57, v55, v61, s[8:9]
	s_waitcnt lgkmcnt(8)
; #define LAS __attribute__((address_space(3)))
; __device__ __forceinline__ float row16_sum(float x) { x += dpp_mov<0xB1>(x); x += dpp_mov<0x4E>(x); x += dpp_mov<0x124>(x); x += dpp_mov<0x128>(x); return x; }
; __device__ __forceinline__ void scan_stage(const u32x2 (&pz)[8], LAS float* buf, float* RKB, size_t mrow0, int t0, int tid, int h, int half, ...
;     ...
;     if (half == 0 && cgp == 0) RKB[(mrow0 + t0 + tl) * 8 + h] = rkb;
;     LAS float* sb = buf + tl * SST + 4 * cgp;
;     *(LAS f32x4*)(sb) = kkn; *(LAS f32x4*)(sb + 64) = nb; *(LAS f32x4*)(sb + 128) = w; *(LAS f32x4*)(sb + 192) = k2; *(LAS f32x4*)(sb + 256) = r;
;     if ((cgp >> 3) == half) *(LAS f32x4*)(buf + tl * SST + 320 + 4 * (cgp & 7)) = v;
; __device__ __forceinline__ void scan_phase(const KAS Args& a, LAS unsigned char* lds, int i, const int tid_, const int bid, const int nblk) {
;     ...
;                 for (int t = 0; t < TC; ++t) {
;                     f32x4 kk4n = kk4, nb4n = nb4, w4n = w4, k4n = k4, r4n = r4; float vn = v;
;                     if (t + 1 < TC) { const LAS float* sn = sb + (t + 1) * SST;
;                         kk4n = *(const LAS f32x4*)(sn); nb4n = *(const LAS f32x4*)(sn + 64); w4n = *(const LAS f32x4*)(sn + 128); k4n = *(const LAS f32x4*)(sn + 192); r4n = *(const LAS f32x4*)(sn + 256); vn = vb[(t + 1) * SST]; }
;                     __builtin_amdgcn_sched_barrier(0x6);
;                     float sa = fmaf(S[3], kk4[3], fmaf(S[2], kk4[2], fmaf(S[1], kk4[1], S[0] * kk4[0])));
;                     const f32x4 Tm = S * w4 + k4 * v;
;                     sa = row16_sum(sa);
;                     S = Tm + nb4 * sa;
;                     float y = fmaf(S[3], r4[3], fmaf(S[2], r4[2], fmaf(S[1], r4[1], S[0] * r4[0]))); y = row16_sum(y);
;                     ysel = (cgp == (t & 15)) ? y : ysel;
;                     if ((t & 15) == 15) yb[(t - 15 + cgp) * 32 + rl] = ysel;
;                     kk4 = kk4n; nb4 = nb4n; w4 = w4n; k4 = k4n; r4 = r4n; v = vn; }
	v_pk_fma_f32 v[36:37], v[164:165], v[2:3], v[40:41] op_sel_hi:[1,0,1]
	v_pk_fma_f32 v[38:39], v[166:167], v[2:3], v[42:43] op_sel_hi:[1,0,1]
	v_add_f32_dpp v58, v57, v56 quad_perm:[1,0,3,2] row_mask:0xf bank_mask:0xf bound_ctrl:1
	v_cndmask_b32_e64 v56, v53, v58, s[10:11]
	v_cndmask_b32_e64 v57, v58, v53, s[10:11]
	v_mul_f32_e32 v44, v36, v188
	v_mul_f32_e32 v59, v176, v36
	v_add_f32_dpp v54, v57, v56 quad_perm:[2,3,0,1] row_mask:0xf bank_mask:0xf bound_ctrl:1
	v_fmac_f32_e32 v44, v37, v189
	v_fmac_f32_e32 v59, v37, v177
	v_fmac_f32_e32 v44, v38, v190
	v_fmac_f32_e32 v59, v38, v178
	v_fmac_f32_e32 v44, v39, v191
	v_fmac_f32_e32 v59, v39, v179
	v_pk_mul_f32 v[40:41], v[200:201], v[208:209] op_sel_hi:[1,0]
	v_pk_mul_f32 v[42:43], v[202:203], v[208:209] op_sel_hi:[1,0]
	v_add_f32_dpp v2, v44, v44 quad_perm:[1,0,3,2] row_mask:0xf bank_mask:0xf bound_ctrl:1
	v_pk_fma_f32 v[40:41], v[36:37], v[196:197], v[40:41]
	v_pk_fma_f32 v[42:43], v[38:39], v[198:199], v[42:43]
	v_add_f32_dpp v2, v2, v2 quad_perm:[2,3,0,1] row_mask:0xf bank_mask:0xf bound_ctrl:1
	ds_read_b128 v[160:163], v124 offset:43648
	ds_read_b128 v[164:167], v124 offset:43904
	ds_read_b128 v[168:171], v124 offset:44160
	v_add_f32_dpp v2, v2, v2 row_ror:4 row_mask:0xf bank_mask:0xf bound_ctrl:1
	ds_read_b128 v[172:175], v124 offset:44416
	ds_read_b128 v[176:179], v124 offset:44672
	ds_read_b32 v158, v110 offset:44928
	v_add_f32_dpp v2, v2, v2 row_ror:8 row_mask:0xf bank_mask:0xf bound_ctrl:1
	s_waitcnt lgkmcnt(6)
	v_pk_fma_f32 v[36:37], v[192:193], v[2:3], v[40:41] op_sel_hi:[1,0,1]
	v_pk_fma_f32 v[38:39], v[194:195], v[2:3], v[42:43] op_sel_hi:[1,0,1]
	v_mul_f32_e32 v44, v36, v136
	v_mul_f32_e32 v60, v204, v36
	v_fmac_f32_e32 v44, v37, v137
	v_fmac_f32_e32 v60, v37, v205
	v_fmac_f32_e32 v44, v38, v138
	v_fmac_f32_e32 v60, v38, v206
	v_fmac_f32_e32 v44, v39, v139
	v_fmac_f32_e32 v60, v39, v207
	v_pk_mul_f32 v[40:41], v[148:149], v[156:157] op_sel_hi:[1,0]
	v_pk_mul_f32 v[42:43], v[150:151], v[156:157] op_sel_hi:[1,0]
	v_add_f32_dpp v2, v44, v44 quad_perm:[1,0,3,2] row_mask:0xf bank_mask:0xf bound_ctrl:1
	v_pk_fma_f32 v[40:41], v[36:37], v[144:145], v[40:41]
	v_pk_fma_f32 v[42:43], v[38:39], v[146:147], v[42:43]
	v_add_f32_dpp v2, v2, v2 quad_perm:[2,3,0,1] row_mask:0xf bank_mask:0xf bound_ctrl:1
	v_cndmask_b32_e64 v56, v59, v60, s[8:9]
	v_cndmask_b32_e64 v57, v60, v59, s[8:9]
	v_add_f32_dpp v2, v2, v2 row_ror:4 row_mask:0xf bank_mask:0xf bound_ctrl:1
	s_nop 0
	v_add_f32_dpp v62, v57, v56 quad_perm:[1,0,3,2] row_mask:0xf bank_mask:0xf bound_ctrl:1
	v_add_f32_dpp v2, v2, v2 row_ror:8 row_mask:0xf bank_mask:0xf bound_ctrl:1
	s_waitcnt lgkmcnt(0)
	v_pk_fma_f32 v[36:37], v[140:141], v[2:3], v[40:41] op_sel_hi:[1,0,1]
	v_pk_fma_f32 v[38:39], v[142:143], v[2:3], v[42:43] op_sel_hi:[1,0,1]
	v_mul_f32_e32 v44, v36, v160
	v_mul_f32_e32 v51, v152, v36
	v_fmac_f32_e32 v44, v37, v161
	v_fmac_f32_e32 v51, v37, v153
	v_fmac_f32_e32 v44, v38, v162
	v_fmac_f32_e32 v51, v38, v154
	v_fmac_f32_e32 v44, v39, v163
	v_fmac_f32_e32 v51, v39, v155
	v_pk_mul_f32 v[40:41], v[172:173], v[158:159] op_sel_hi:[1,0]
	v_pk_mul_f32 v[42:43], v[174:175], v[158:159] op_sel_hi:[1,0]
	v_add_f32_dpp v2, v44, v44 quad_perm:[1,0,3,2] row_mask:0xf bank_mask:0xf bound_ctrl:1
	v_pk_fma_f32 v[40:41], v[36:37], v[168:169], v[40:41]
	v_pk_fma_f32 v[42:43], v[38:39], v[170:171], v[42:43]
	v_add_f32_dpp v2, v2, v2 quad_perm:[2,3,0,1] row_mask:0xf bank_mask:0xf bound_ctrl:1
	s_nop 0
	s_nop 0
	v_add_f32_dpp v2, v2, v2 row_ror:4 row_mask:0xf bank_mask:0xf bound_ctrl:1
	s_nop 0
	s_nop 0
	v_add_f32_dpp v2, v2, v2 row_ror:8 row_mask:0xf bank_mask:0xf bound_ctrl:1
	v_pk_fma_f32 v[36:37], v[164:165], v[2:3], v[40:41] op_sel_hi:[1,0,1]
	v_pk_fma_f32 v[38:39], v[166:167], v[2:3], v[42:43] op_sel_hi:[1,0,1]
	v_mul_f32_e32 v63, v176, v36
	v_fmac_f32_e32 v63, v37, v177
	v_fmac_f32_e32 v63, v38, v178
	v_fmac_f32_e32 v63, v39, v179
	v_cndmask_b32_e64 v56, v51, v63, s[8:9]
	v_cndmask_b32_e64 v57, v63, v51, s[8:9]
	s_nop 0
	s_nop 0
	v_add_f32_dpp v66, v57, v56 quad_perm:[1,0,3,2] row_mask:0xf bank_mask:0xf bound_ctrl:1
	v_cndmask_b32_e64 v56, v62, v66, s[10:11]
	v_cndmask_b32_e64 v57, v66, v62, s[10:11]
	s_nop 0
	s_nop 0
	v_add_f32_dpp v64, v57, v56 quad_perm:[2,3,0,1] row_mask:0xf bank_mask:0xf bound_ctrl:1
	v_cndmask_b32_e64 v56, v54, v64, s[12:13]
	v_cndmask_b32_e64 v57, v64, v54, s[12:13]
	s_nop 0
	s_nop 0
	v_add_f32_dpp v46, v57, v56 row_shl:4 row_mask:0xf bank_mask:0x5
	s_nop 0
	s_nop 0
	v_add_f32_dpp v46, v57, v56 row_shr:4 row_mask:0xf bank_mask:0xa
	v_cndmask_b32_e64 v56, v49, v46, s[14:15]
	v_cndmask_b32_e64 v57, v46, v49, s[14:15]
	s_nop 0
	s_nop 0
	v_add_f32_dpp v48, v57, v56 row_ror:8 row_mask:0xf bank_mask:0xf bound_ctrl:1
	ds_write_b32 v122, v48 offset:2048
	s_cbranch_vccnz .LBB0_183
	s_and_saveexec_b64 s[2:3], s[42:43]
	s_cbranch_execz .Lsc_nost
	v_lshl_add_u64 v[52:53], s[88:89], 0, v[100:101]
	global_store_dword v[52:53], v245, off
.Lsc_nost:
	s_or_b64 exec, exec, s[2:3]
	s_and_saveexec_b64 s[2:3], s[44:45]
	s_cbranch_execz .LBB0_182
	v_lshlrev_b32_e32 v28, 16, v84
	v_and_b32_e32 v29, 0xffff0000, v84
	v_lshlrev_b32_e32 v30, 16, v90
	v_and_b32_e32 v31, 0xffff0000, v90
	v_pk_add_f32 v[30:31], v[30:31], v[28:29] neg_lo:[0,1] neg_hi:[0,1]
	v_lshlrev_b32_e32 v32, 16, v91
	v_pk_fma_f32 v[28:29], v[8:9], v[30:31], v[28:29]
	v_lshlrev_b32_e32 v30, 16, v85
	v_and_b32_e32 v31, 0xffff0000, v85
	v_and_b32_e32 v33, 0xffff0000, v91
	v_pk_add_f32 v[32:33], v[32:33], v[30:31] neg_lo:[0,1] neg_hi:[0,1]
	v_lshl_add_u32 v2, v116, 2, v228
	v_pk_fma_f32 v[30:31], v[10:11], v[32:33], v[30:31]
	ds_write_b128 v2, v[28:31] offset:1280
	s_branch .LBB0_182
